# adds P2-P3 per-row-panel arrival counters (write-through o and z stores, no grid barrier)
# speedup vs baseline: 1.0470x; 1.0138x over previous
; __device__ __forceinline__ u32x4 pack8(const f32x4 v0, const f32x4 v1) { u32x4 w; w.x = cvt_pk_bf16(v0[0], v0[1]); w.y = cvt_pk_bf16(v0[2], v0[3]); w.z = cvt_pk_bf16(v1[0], v1[1]); w.w = cvt_pk_bf16(v1[2], v1[3]); return w; }
; __device__ __forceinline__ void unpack8(const u32x4 w, f32x4& v0, f32x4& v1) { v0 = (f32x4){bf_lo(w.x), bf_hi(w.x), bf_lo(w.y), bf_hi(w.y)}; v1 = (f32x4){bf_lo(w.z), bf_hi(w.z), bf_lo(w.w), bf_hi(w.w)}; }
; __device__ __forceinline__ float shfl_xor_l(float v, int mask, int lane) { return __builtin_bit_cast(float, __builtin_amdgcn_ds_bpermute((lane ^ mask) << 2, __builtin_bit_cast(int, v))); }
; __global__ void __launch_bounds__(NWAVES * 64, 2) mk_fwd(Args a) {
;     ...
;                 asm volatile("s_waitcnt vmcnt(0)" ::: "memory");
;                 int tl_ = threadIdx.x; asm volatile("" : "+v"(tl_)); const int ln = tl_ & 63;
;                 const int c8 = (ln & 15) * 8;
;                 const f32x4 sw0 = *(const f32x4*)(sw + c8), sw1 = *(const f32x4*)(sw + c8 + 4);
;                 const size_t R0 = (size_t)b * SEQL + 256 * qb + 32 * wave;
;                 const size_t offc = (R0 + (ln >> 4)) * DMOD + 128 * h + c8;
;                 v4u va[8], vb[8];
; #pragma unroll
;                 for (int it = 0; it < 8; ++it) { va[it] = *(const v4u*)(O1 + offc + (size_t)(4 * it) * DMOD); vb[it] = *(const v4u*)(O2 + offc + (size_t)(4 * it) * DMOD); }
; #pragma unroll
;                 for (int it = 0; it < 8; ++it) {
;                     f32x4 a0, a1, b0, b1; unpack8(va[it], a0, a1); unpack8(vb[it], b0, b1);
;                     const f32x4 d0 = a0 - b0 * lam, d1 = a1 - b1 * lam;
;                     float ss = (d0[0] * d0[0] + d0[1] * d0[1]) + (d0[2] * d0[2] + d0[3] * d0[3]) + (d1[0] * d1[0] + d1[1] * d1[1]) + (d1[2] * d1[2] + d1[3] * d1[3]);
;                     ss += pg8::shfl_xor_l(ss, 1, ln); ss += pg8::shfl_xor_l(ss, 2, ln); ss += pg8::shfl_xor_l(ss, 4, ln); ss += pg8::shfl_xor_l(ss, 8, ln);
;                     const float rs = osc * __builtin_amdgcn_rsqf(ss * (1.0f / 128.0f) + 1e-6f);
;                     *(v4u*)(Qb + offc + (size_t)(4 * it) * DMOD) = pack8(d0 * rs * sw0, d1 * rs * sw1);
.LBB0_248:
	v_mov_b32_e32 v0, v244
	v_readlane_b32 s1, v255, 18
	s_waitcnt vmcnt(0)
	s_add_i32 s1, s80, s1
	v_and_b32_e32 v76, 63, v0
	v_lshlrev_b32_e32 v2, 3, v0
	s_add_i32 s1, s1, s81
	v_bfe_u32 v0, v0, 4, 2
	v_or_b32_e32 v0, s1, v0
	v_lshlrev_b64 v[10:11], 10, v[0:1]
	v_and_b32_e32 v12, 0x78, v2
	v_or_b32_e32 v0, s79, v10
	v_or_b32_e32 v10, v0, v12
	v_readlane_b32 s2, v255, 47
	v_lshlrev_b64 v[74:75], 1, v[10:11]
	v_lshlrev_b32_e32 v6, 2, v12
	v_readlane_b32 s3, v255, 48
	v_lshl_add_u64 v[10:11], s[14:15], 0, v[74:75]
	s_nop 3
	global_load_dwordx4 v[2:5], v6, s[2:3] offset:16
	s_nop 0
	global_load_dwordx4 v[6:9], v6, s[2:3]
	v_lshl_add_u64 v[12:13], s[86:87], 0, v[74:75]
	global_load_dwordx4 v[70:73], v[10:11], off
	global_load_dwordx4 v[66:69], v[12:13], off
	v_add_co_u32_e32 v14, vcc, s61, v10
	s_movk_i32 s1, 0x4000
	s_nop 0
	v_addc_co_u32_e32 v15, vcc, 0, v11, vcc
	global_load_dwordx4 v[62:65], v[14:15], off
	v_add_co_u32_e32 v14, vcc, s61, v12
	v_lshlrev_b32_e32 v0, 2, v76
	s_nop 0
	v_addc_co_u32_e32 v15, vcc, 0, v13, vcc
	global_load_dwordx4 v[58:61], v[14:15], off
	v_add_co_u32_e32 v14, vcc, s1, v10
	v_xor_b32_e32 v78, 4, v0
	s_nop 0
	v_addc_co_u32_e32 v15, vcc, 0, v11, vcc
	global_load_dwordx4 v[54:57], v[14:15], off
	v_add_co_u32_e32 v14, vcc, s1, v12
	v_xor_b32_e32 v77, 8, v0
	s_nop 0
	v_addc_co_u32_e32 v15, vcc, 0, v13, vcc
	global_load_dwordx4 v[50:53], v[14:15], off
	v_xor_b32_e32 v76, 16, v0
	v_xor_b32_e32 v0, 32, v0
	s_movk_i32 s2, 0x6000
	v_lshl_add_u64 v[74:75], s[6:7], 0, v[74:75]
	v_add_co_u32_e32 v14, vcc, s2, v10
	s_mov_b32 s3, 0x8000
	s_nop 0
	v_addc_co_u32_e32 v15, vcc, 0, v11, vcc
	global_load_dwordx4 v[46:49], v[14:15], off
	v_add_co_u32_e32 v14, vcc, s2, v12
	s_mov_b32 s4, 0xa000
	s_nop 0
	v_addc_co_u32_e32 v15, vcc, 0, v13, vcc
	global_load_dwordx4 v[42:45], v[14:15], off
	v_add_co_u32_e32 v14, vcc, s3, v10
	s_mov_b32 s12, 0xc000
	s_nop 0
	v_addc_co_u32_e32 v15, vcc, 0, v11, vcc
	global_load_dwordx4 v[38:41], v[14:15], off
	v_add_co_u32_e32 v14, vcc, s3, v12
	s_mov_b32 s13, 0xe000
	s_nop 0
	v_addc_co_u32_e32 v15, vcc, 0, v13, vcc
	global_load_dwordx4 v[34:37], v[14:15], off
	v_add_co_u32_e32 v14, vcc, s4, v10
	v_readlane_b32 s80, v253, 50
	s_nop 0
	v_addc_co_u32_e32 v15, vcc, 0, v11, vcc
	global_load_dwordx4 v[30:33], v[14:15], off
	v_add_co_u32_e32 v14, vcc, s4, v12
	s_add_i32 s64, s64, 2
	s_nop 0
	v_addc_co_u32_e32 v15, vcc, 0, v13, vcc
	global_load_dwordx4 v[26:29], v[14:15], off
	v_add_co_u32_e32 v14, vcc, s12, v10
	s_add_i32 s78, s78, s80
	s_nop 0
	v_addc_co_u32_e32 v15, vcc, 0, v11, vcc
	global_load_dwordx4 v[22:25], v[14:15], off
	v_add_co_u32_e32 v14, vcc, s12, v12
	s_mov_b32 s88, 0x8000
	s_nop 0
	v_addc_co_u32_e32 v15, vcc, 0, v13, vcc
	v_add_co_u32_e32 v10, vcc, s13, v10
	global_load_dwordx4 v[18:21], v[14:15], off
	s_waitcnt vmcnt(13)
	v_lshlrev_b32_e32 v80, 16, v70
	s_waitcnt vmcnt(12)
	v_lshlrev_b32_e32 v84, 16, v66
	v_and_b32_e32 v85, 0xffff0000, v66
	v_xor_b32_e32 v66, 0x80000000, v236
	v_and_b32_e32 v81, 0xffff0000, v70
	v_lshlrev_b32_e32 v70, 16, v71
	v_and_b32_e32 v71, 0xffff0000, v71
	v_lshlrev_b32_e32 v86, 16, v67
	v_and_b32_e32 v87, 0xffff0000, v67
	v_mov_b32_e32 v67, v66
	v_lshlrev_b32_e32 v82, 16, v72
	v_and_b32_e32 v83, 0xffff0000, v72
	v_lshlrev_b32_e32 v72, 16, v73
	v_and_b32_e32 v73, 0xffff0000, v73
	v_lshlrev_b32_e32 v88, 16, v68
	v_and_b32_e32 v89, 0xffff0000, v68
	v_lshlrev_b32_e32 v68, 16, v69
	v_and_b32_e32 v69, 0xffff0000, v69
	v_pk_fma_f32 v[80:81], v[236:237], v[84:85], v[80:81] neg_lo:[1,0,0] neg_hi:[1,0,0]
	v_pk_fma_f32 v[70:71], v[66:67], v[86:87], v[70:71]
	v_pk_fma_f32 v[68:69], v[66:67], v[68:69], v[72:73]
	v_pk_mul_f32 v[72:73], v[70:71], v[70:71]
	v_pk_mul_f32 v[84:85], v[80:81], v[80:81]
	v_pk_fma_f32 v[82:83], v[236:237], v[88:89], v[82:83] neg_lo:[1,0,0] neg_hi:[1,0,0]
	v_pk_mov_b32 v[86:87], v[84:85], v[72:73] op_sel:[1,0]
	v_mov_b32_e32 v85, v73
	v_pk_add_f32 v[72:73], v[86:87], v[84:85]
	v_pk_mul_f32 v[84:85], v[68:69], v[68:69]
	v_pk_mul_f32 v[86:87], v[82:83], v[82:83]
	v_mov_b32_e32 v88, v84
	v_mov_b32_e32 v89, v86
	v_mov_b32_e32 v86, v85
	v_pk_add_f32 v[84:85], v[88:89], v[86:87]
	v_add_f32_e32 v72, v72, v73
	v_add_f32_e32 v72, v85, v72
	v_add_f32_e32 v72, v84, v72
	ds_bpermute_b32 v73, v78, v72
	v_addc_co_u32_e32 v11, vcc, 0, v11, vcc
	global_load_dwordx4 v[14:17], v[10:11], off
	v_add_co_u32_e32 v10, vcc, s13, v12
	s_waitcnt lgkmcnt(0)
	v_add_f32_e32 v72, v72, v73
	ds_bpermute_b32 v73, v77, v72
	v_addc_co_u32_e32 v11, vcc, 0, v13, vcc
	global_load_dwordx4 v[10:13], v[10:11], off
	s_mov_b32 s27, 0xa000
	s_waitcnt lgkmcnt(0)
	v_add_f32_e32 v72, v72, v73
	ds_bpermute_b32 v73, v76, v72
	s_mov_b32 s26, 0xc000
	v_readlane_b32 s81, v253, 51
	s_waitcnt lgkmcnt(0)
	v_add_f32_e32 v72, v72, v73
	ds_bpermute_b32 v73, v0, v72
	s_waitcnt lgkmcnt(0)
	v_add_f32_e32 v72, v72, v73
	v_fmamk_f32 v72, v72, 0x3c000000, v245
	v_rsq_f32_e32 v72, v72
	s_nop 0
	v_mul_f32_e32 v72, v249, v72
	v_pk_mul_f32 v[80:81], v[80:81], v[72:73] op_sel_hi:[1,0]
	v_pk_mul_f32 v[70:71], v[70:71], v[72:73] op_sel_hi:[1,0]
	v_pk_mul_f32 v[82:83], v[82:83], v[72:73] op_sel_hi:[1,0]
	v_pk_mul_f32 v[68:69], v[68:69], v[72:73] op_sel_hi:[1,0]
	v_pk_mul_f32 v[70:71], v[8:9], v[70:71]
	v_pk_mul_f32 v[80:81], v[6:7], v[80:81]
	v_pk_mul_f32 v[72:73], v[4:5], v[68:69]
	v_pk_mul_f32 v[82:83], v[2:3], v[82:83]
	v_cvt_pk_bf16_f32 v68, v80, v81
	v_cvt_pk_bf16_f32 v69, v70, v71
	v_cvt_pk_bf16_f32 v70, v82, v83
	v_cvt_pk_bf16_f32 v71, v72, v73
	global_store_dwordx4 v[74:75], v[68:71], off sc1
	s_waitcnt vmcnt(13)
; __device__ __forceinline__ u32x4 pack8(const f32x4 v0, const f32x4 v1) { u32x4 w; w.x = cvt_pk_bf16(v0[0], v0[1]); w.y = cvt_pk_bf16(v0[2], v0[3]); w.z = cvt_pk_bf16(v1[0], v1[1]); w.w = cvt_pk_bf16(v1[2], v1[3]); return w; }
; __device__ __forceinline__ void unpack8(const u32x4 w, f32x4& v0, f32x4& v1) { v0 = (f32x4){bf_lo(w.x), bf_hi(w.x), bf_lo(w.y), bf_hi(w.y)}; v1 = (f32x4){bf_lo(w.z), bf_hi(w.z), bf_lo(w.w), bf_hi(w.w)}; }
; __device__ __forceinline__ float shfl_xor_l(float v, int mask, int lane) { return __builtin_bit_cast(float, __builtin_amdgcn_ds_bpermute((lane ^ mask) << 2, __builtin_bit_cast(int, v))); }
; __global__ void __launch_bounds__(NWAVES * 64, 2) mk_fwd(Args a) {
;     ...
;                 for (int it = 0; it < 8; ++it) {
;                     f32x4 a0, a1, b0, b1; unpack8(va[it], a0, a1); unpack8(vb[it], b0, b1);
;                     const f32x4 d0 = a0 - b0 * lam, d1 = a1 - b1 * lam;
;                     float ss = (d0[0] * d0[0] + d0[1] * d0[1]) + (d0[2] * d0[2] + d0[3] * d0[3]) + (d1[0] * d1[0] + d1[1] * d1[1]) + (d1[2] * d1[2] + d1[3] * d1[3]);
;                     ss += pg8::shfl_xor_l(ss, 1, ln); ss += pg8::shfl_xor_l(ss, 2, ln); ss += pg8::shfl_xor_l(ss, 4, ln); ss += pg8::shfl_xor_l(ss, 8, ln);
;                     const float rs = osc * __builtin_amdgcn_rsqf(ss * (1.0f / 128.0f) + 1e-6f);
;                     *(v4u*)(Qb + offc + (size_t)(4 * it) * DMOD) = pack8(d0 * rs * sw0, d1 * rs * sw1);
	v_lshlrev_b32_e32 v72, 16, v58
	v_and_b32_e32 v73, 0xffff0000, v58
	v_lshlrev_b32_e32 v68, 16, v62
	v_and_b32_e32 v69, 0xffff0000, v62
	v_lshlrev_b32_e32 v62, 16, v63
	v_and_b32_e32 v63, 0xffff0000, v63
	v_lshlrev_b32_e32 v58, 16, v59
	v_and_b32_e32 v59, 0xffff0000, v59
	v_lshlrev_b32_e32 v70, 16, v64
	v_and_b32_e32 v71, 0xffff0000, v64
	v_lshlrev_b32_e32 v64, 16, v65
	v_and_b32_e32 v65, 0xffff0000, v65
	v_lshlrev_b32_e32 v80, 16, v60
	v_and_b32_e32 v81, 0xffff0000, v60
	v_lshlrev_b32_e32 v60, 16, v61
	v_and_b32_e32 v61, 0xffff0000, v61
	v_pk_fma_f32 v[68:69], v[236:237], v[72:73], v[68:69] neg_lo:[1,0,0] neg_hi:[1,0,0]
	v_pk_fma_f32 v[58:59], v[66:67], v[58:59], v[62:63]
	v_pk_fma_f32 v[62:63], v[236:237], v[80:81], v[70:71] neg_lo:[1,0,0] neg_hi:[1,0,0]
	v_pk_fma_f32 v[60:61], v[66:67], v[60:61], v[64:65]
	v_pk_mul_f32 v[64:65], v[58:59], v[58:59]
	v_pk_mul_f32 v[70:71], v[68:69], v[68:69]
	s_nop 0
	v_pk_mov_b32 v[72:73], v[70:71], v[64:65] op_sel:[1,0]
	v_mov_b32_e32 v71, v65
	v_pk_add_f32 v[64:65], v[72:73], v[70:71]
	v_pk_mul_f32 v[70:71], v[60:61], v[60:61]
	v_pk_mul_f32 v[72:73], v[62:63], v[62:63]
	v_mov_b32_e32 v80, v70
	v_mov_b32_e32 v81, v72
	v_mov_b32_e32 v72, v71
	v_pk_add_f32 v[70:71], v[80:81], v[72:73]
	v_add_f32_e32 v64, v64, v65
	v_add_f32_e32 v64, v71, v64
	v_add_f32_e32 v64, v70, v64
	ds_bpermute_b32 v65, v78, v64
	s_waitcnt lgkmcnt(0)
	v_add_f32_e32 v64, v64, v65
	ds_bpermute_b32 v65, v77, v64
	s_waitcnt lgkmcnt(0)
	v_add_f32_e32 v64, v64, v65
	ds_bpermute_b32 v65, v76, v64
	s_waitcnt lgkmcnt(0)
	v_add_f32_e32 v64, v64, v65
	ds_bpermute_b32 v65, v0, v64
	s_waitcnt lgkmcnt(0)
	v_add_f32_e32 v64, v64, v65
	v_fmamk_f32 v64, v64, 0x3c000000, v245
	v_rsq_f32_e32 v64, v64
	s_nop 0
	v_mul_f32_e32 v64, v249, v64
	v_pk_mul_f32 v[68:69], v[68:69], v[64:65] op_sel_hi:[1,0]
	v_pk_mul_f32 v[58:59], v[58:59], v[64:65] op_sel_hi:[1,0]
	v_pk_mul_f32 v[62:63], v[62:63], v[64:65] op_sel_hi:[1,0]
	v_pk_mul_f32 v[60:61], v[60:61], v[64:65] op_sel_hi:[1,0]
	v_pk_mul_f32 v[70:71], v[8:9], v[58:59]
	v_pk_mul_f32 v[58:59], v[6:7], v[68:69]
	v_pk_mul_f32 v[64:65], v[4:5], v[60:61]
	v_pk_mul_f32 v[60:61], v[2:3], v[62:63]
	v_add_co_u32_e32 v62, vcc, s61, v74
	v_cvt_pk_bf16_f32 v58, v58, v59
	v_cvt_pk_bf16_f32 v59, v70, v71
	v_cvt_pk_bf16_f32 v60, v60, v61
	v_cvt_pk_bf16_f32 v61, v64, v65
	v_addc_co_u32_e32 v63, vcc, 0, v75, vcc
	global_store_dwordx4 v[62:63], v[58:61], off sc1
	s_waitcnt vmcnt(12)
	v_lshlrev_b32_e32 v62, 16, v50
	v_and_b32_e32 v63, 0xffff0000, v50
	v_lshlrev_b32_e32 v58, 16, v54
	v_and_b32_e32 v59, 0xffff0000, v54
	v_lshlrev_b32_e32 v54, 16, v55
	v_and_b32_e32 v55, 0xffff0000, v55
	v_lshlrev_b32_e32 v50, 16, v51
	v_and_b32_e32 v51, 0xffff0000, v51
	v_lshlrev_b32_e32 v60, 16, v56
	v_and_b32_e32 v61, 0xffff0000, v56
	v_lshlrev_b32_e32 v56, 16, v57
	v_and_b32_e32 v57, 0xffff0000, v57
	v_lshlrev_b32_e32 v64, 16, v52
	v_and_b32_e32 v65, 0xffff0000, v52
	v_lshlrev_b32_e32 v52, 16, v53
	v_and_b32_e32 v53, 0xffff0000, v53
	v_pk_fma_f32 v[58:59], v[236:237], v[62:63], v[58:59] neg_lo:[1,0,0] neg_hi:[1,0,0]
	v_pk_fma_f32 v[50:51], v[66:67], v[50:51], v[54:55]
	v_pk_fma_f32 v[54:55], v[236:237], v[64:65], v[60:61] neg_lo:[1,0,0] neg_hi:[1,0,0]
	v_pk_fma_f32 v[52:53], v[66:67], v[52:53], v[56:57]
	v_pk_mul_f32 v[56:57], v[50:51], v[50:51]
	v_pk_mul_f32 v[60:61], v[58:59], v[58:59]
	s_nop 0
	v_pk_mov_b32 v[62:63], v[60:61], v[56:57] op_sel:[1,0]
	v_mov_b32_e32 v61, v57
	v_pk_add_f32 v[56:57], v[62:63], v[60:61]
	v_pk_mul_f32 v[60:61], v[52:53], v[52:53]
	v_pk_mul_f32 v[62:63], v[54:55], v[54:55]
	v_mov_b32_e32 v64, v60
	v_mov_b32_e32 v65, v62
	v_mov_b32_e32 v62, v61
	v_pk_add_f32 v[60:61], v[64:65], v[62:63]
	v_add_f32_e32 v56, v56, v57
	v_add_f32_e32 v56, v61, v56
	v_add_f32_e32 v56, v60, v56
	ds_bpermute_b32 v57, v78, v56
	s_waitcnt lgkmcnt(0)
	v_add_f32_e32 v56, v56, v57
	ds_bpermute_b32 v57, v77, v56
	s_waitcnt lgkmcnt(0)
	v_add_f32_e32 v56, v56, v57
	ds_bpermute_b32 v57, v76, v56
	s_waitcnt lgkmcnt(0)
	v_add_f32_e32 v56, v56, v57
	ds_bpermute_b32 v57, v0, v56
	s_waitcnt lgkmcnt(0)
	v_add_f32_e32 v56, v56, v57
	v_fmamk_f32 v56, v56, 0x3c000000, v245
	v_rsq_f32_e32 v56, v56
	s_nop 0
	v_mul_f32_e32 v56, v249, v56
	v_pk_mul_f32 v[58:59], v[58:59], v[56:57] op_sel_hi:[1,0]
	v_pk_mul_f32 v[50:51], v[50:51], v[56:57] op_sel_hi:[1,0]
	v_pk_mul_f32 v[54:55], v[54:55], v[56:57] op_sel_hi:[1,0]
	v_pk_mul_f32 v[52:53], v[52:53], v[56:57] op_sel_hi:[1,0]
	v_pk_mul_f32 v[60:61], v[8:9], v[50:51]
	v_pk_mul_f32 v[50:51], v[6:7], v[58:59]
	v_pk_mul_f32 v[56:57], v[4:5], v[52:53]
	v_pk_mul_f32 v[52:53], v[2:3], v[54:55]
	v_add_co_u32_e32 v54, vcc, s1, v74
	v_cvt_pk_bf16_f32 v50, v50, v51
	v_cvt_pk_bf16_f32 v51, v60, v61
	v_cvt_pk_bf16_f32 v52, v52, v53
	v_cvt_pk_bf16_f32 v53, v56, v57
	v_addc_co_u32_e32 v55, vcc, 0, v75, vcc
	global_store_dwordx4 v[54:55], v[50:53], off sc1
	s_waitcnt vmcnt(11)
	v_lshlrev_b32_e32 v54, 16, v42
	v_and_b32_e32 v55, 0xffff0000, v42
	v_lshlrev_b32_e32 v50, 16, v46
	v_and_b32_e32 v51, 0xffff0000, v46
	v_lshlrev_b32_e32 v46, 16, v47
	v_and_b32_e32 v47, 0xffff0000, v47
	v_lshlrev_b32_e32 v42, 16, v43
	v_and_b32_e32 v43, 0xffff0000, v43
	v_lshlrev_b32_e32 v52, 16, v48
	v_and_b32_e32 v53, 0xffff0000, v48
	v_lshlrev_b32_e32 v48, 16, v49
	v_and_b32_e32 v49, 0xffff0000, v49
	v_lshlrev_b32_e32 v56, 16, v44
	v_and_b32_e32 v57, 0xffff0000, v44
	v_lshlrev_b32_e32 v44, 16, v45
	v_and_b32_e32 v45, 0xffff0000, v45
	v_pk_fma_f32 v[50:51], v[236:237], v[54:55], v[50:51] neg_lo:[1,0,0] neg_hi:[1,0,0]
	v_pk_fma_f32 v[42:43], v[66:67], v[42:43], v[46:47]
	v_pk_fma_f32 v[46:47], v[236:237], v[56:57], v[52:53] neg_lo:[1,0,0] neg_hi:[1,0,0]
	v_pk_fma_f32 v[44:45], v[66:67], v[44:45], v[48:49]
	v_pk_mul_f32 v[48:49], v[42:43], v[42:43]
	v_pk_mul_f32 v[52:53], v[50:51], v[50:51]
	v_readlane_b32 s1, v255, 20
	v_pk_mov_b32 v[54:55], v[52:53], v[48:49] op_sel:[1,0]
	v_mov_b32_e32 v53, v49
	v_pk_add_f32 v[48:49], v[54:55], v[52:53]
	v_pk_mul_f32 v[52:53], v[44:45], v[44:45]
	v_pk_mul_f32 v[54:55], v[46:47], v[46:47]
	v_mov_b32_e32 v56, v52
	v_mov_b32_e32 v57, v54
	v_mov_b32_e32 v54, v53
	v_pk_add_f32 v[52:53], v[56:57], v[54:55]
	v_add_f32_e32 v48, v48, v49
	v_add_f32_e32 v48, v53, v48
	v_add_f32_e32 v48, v52, v48
	ds_bpermute_b32 v49, v78, v48
	s_add_i32 s77, s77, s1
	s_cmpk_gt_i32 s78, 0x1ff
	s_waitcnt lgkmcnt(0)
; __device__ __forceinline__ u32x4 pack8(const f32x4 v0, const f32x4 v1) { u32x4 w; w.x = cvt_pk_bf16(v0[0], v0[1]); w.y = cvt_pk_bf16(v0[2], v0[3]); w.z = cvt_pk_bf16(v1[0], v1[1]); w.w = cvt_pk_bf16(v1[2], v1[3]); return w; }
; __device__ __forceinline__ void unpack8(const u32x4 w, f32x4& v0, f32x4& v1) { v0 = (f32x4){bf_lo(w.x), bf_hi(w.x), bf_lo(w.y), bf_hi(w.y)}; v1 = (f32x4){bf_lo(w.z), bf_hi(w.z), bf_lo(w.w), bf_hi(w.w)}; }
; __device__ __forceinline__ float shfl_xor_l(float v, int mask, int lane) { return __builtin_bit_cast(float, __builtin_amdgcn_ds_bpermute((lane ^ mask) << 2, __builtin_bit_cast(int, v))); }
; __global__ void __launch_bounds__(NWAVES * 64, 2) mk_fwd(Args a) {
;     ...
;                 for (int it = 0; it < 8; ++it) {
;                     f32x4 a0, a1, b0, b1; unpack8(va[it], a0, a1); unpack8(vb[it], b0, b1);
;                     const f32x4 d0 = a0 - b0 * lam, d1 = a1 - b1 * lam;
;                     float ss = (d0[0] * d0[0] + d0[1] * d0[1]) + (d0[2] * d0[2] + d0[3] * d0[3]) + (d1[0] * d1[0] + d1[1] * d1[1]) + (d1[2] * d1[2] + d1[3] * d1[3]);
;                     ss += pg8::shfl_xor_l(ss, 1, ln); ss += pg8::shfl_xor_l(ss, 2, ln); ss += pg8::shfl_xor_l(ss, 4, ln); ss += pg8::shfl_xor_l(ss, 8, ln);
;                     const float rs = osc * __builtin_amdgcn_rsqf(ss * (1.0f / 128.0f) + 1e-6f);
;                     *(v4u*)(Qb + offc + (size_t)(4 * it) * DMOD) = pack8(d0 * rs * sw0, d1 * rs * sw1);
	v_add_f32_e32 v48, v48, v49
	ds_bpermute_b32 v49, v77, v48
	s_waitcnt lgkmcnt(0)
	v_add_f32_e32 v48, v48, v49
	ds_bpermute_b32 v49, v76, v48
	s_waitcnt lgkmcnt(0)
	v_add_f32_e32 v48, v48, v49
	ds_bpermute_b32 v49, v0, v48
	s_waitcnt lgkmcnt(0)
	v_add_f32_e32 v48, v48, v49
	v_fmamk_f32 v48, v48, 0x3c000000, v245
	v_rsq_f32_e32 v48, v48
	s_nop 0
	v_mul_f32_e32 v48, v249, v48
	v_pk_mul_f32 v[50:51], v[50:51], v[48:49] op_sel_hi:[1,0]
	v_pk_mul_f32 v[42:43], v[42:43], v[48:49] op_sel_hi:[1,0]
	v_pk_mul_f32 v[46:47], v[46:47], v[48:49] op_sel_hi:[1,0]
	v_pk_mul_f32 v[44:45], v[44:45], v[48:49] op_sel_hi:[1,0]
	v_pk_mul_f32 v[52:53], v[8:9], v[42:43]
	v_pk_mul_f32 v[42:43], v[6:7], v[50:51]
	v_pk_mul_f32 v[48:49], v[4:5], v[44:45]
	v_pk_mul_f32 v[44:45], v[2:3], v[46:47]
	v_add_co_u32_e32 v46, vcc, s2, v74
	v_cvt_pk_bf16_f32 v42, v42, v43
	v_cvt_pk_bf16_f32 v43, v52, v53
	v_cvt_pk_bf16_f32 v44, v44, v45
	v_cvt_pk_bf16_f32 v45, v48, v49
	v_addc_co_u32_e32 v47, vcc, 0, v75, vcc
	global_store_dwordx4 v[46:47], v[42:45], off sc1
	s_waitcnt vmcnt(10)
	v_lshlrev_b32_e32 v46, 16, v34
	v_and_b32_e32 v47, 0xffff0000, v34
	v_lshlrev_b32_e32 v42, 16, v38
	v_and_b32_e32 v43, 0xffff0000, v38
	v_lshlrev_b32_e32 v38, 16, v39
	v_and_b32_e32 v39, 0xffff0000, v39
	v_lshlrev_b32_e32 v34, 16, v35
	v_and_b32_e32 v35, 0xffff0000, v35
	v_lshlrev_b32_e32 v44, 16, v40
	v_and_b32_e32 v45, 0xffff0000, v40
	v_lshlrev_b32_e32 v40, 16, v41
	v_and_b32_e32 v41, 0xffff0000, v41
	v_lshlrev_b32_e32 v48, 16, v36
	v_and_b32_e32 v49, 0xffff0000, v36
	v_lshlrev_b32_e32 v36, 16, v37
	v_and_b32_e32 v37, 0xffff0000, v37
	v_pk_fma_f32 v[42:43], v[236:237], v[46:47], v[42:43] neg_lo:[1,0,0] neg_hi:[1,0,0]
	v_pk_fma_f32 v[34:35], v[66:67], v[34:35], v[38:39]
	v_pk_fma_f32 v[38:39], v[236:237], v[48:49], v[44:45] neg_lo:[1,0,0] neg_hi:[1,0,0]
	v_pk_fma_f32 v[36:37], v[66:67], v[36:37], v[40:41]
	v_pk_mul_f32 v[40:41], v[34:35], v[34:35]
	v_pk_mul_f32 v[44:45], v[42:43], v[42:43]
	s_nop 0
	v_pk_mov_b32 v[46:47], v[44:45], v[40:41] op_sel:[1,0]
	v_mov_b32_e32 v45, v41
	v_pk_add_f32 v[40:41], v[46:47], v[44:45]
	v_pk_mul_f32 v[44:45], v[36:37], v[36:37]
	v_pk_mul_f32 v[46:47], v[38:39], v[38:39]
	v_mov_b32_e32 v48, v44
	v_mov_b32_e32 v49, v46
	v_mov_b32_e32 v46, v45
	v_pk_add_f32 v[44:45], v[48:49], v[46:47]
	v_add_f32_e32 v40, v40, v41
	v_add_f32_e32 v40, v45, v40
	v_add_f32_e32 v40, v44, v40
	ds_bpermute_b32 v41, v78, v40
	s_waitcnt lgkmcnt(0)
	v_add_f32_e32 v40, v40, v41
	ds_bpermute_b32 v41, v77, v40
	s_waitcnt lgkmcnt(0)
	v_add_f32_e32 v40, v40, v41
	ds_bpermute_b32 v41, v76, v40
	s_waitcnt lgkmcnt(0)
	v_add_f32_e32 v40, v40, v41
	ds_bpermute_b32 v41, v0, v40
	s_waitcnt lgkmcnt(0)
	v_add_f32_e32 v40, v40, v41
	v_fmamk_f32 v40, v40, 0x3c000000, v245
	v_rsq_f32_e32 v40, v40
	s_nop 0
	v_mul_f32_e32 v40, v249, v40
	v_pk_mul_f32 v[42:43], v[42:43], v[40:41] op_sel_hi:[1,0]
	v_pk_mul_f32 v[34:35], v[34:35], v[40:41] op_sel_hi:[1,0]
	v_pk_mul_f32 v[38:39], v[38:39], v[40:41] op_sel_hi:[1,0]
	v_pk_mul_f32 v[36:37], v[36:37], v[40:41] op_sel_hi:[1,0]
	v_pk_mul_f32 v[44:45], v[8:9], v[34:35]
	v_pk_mul_f32 v[34:35], v[6:7], v[42:43]
	v_pk_mul_f32 v[40:41], v[4:5], v[36:37]
	v_pk_mul_f32 v[36:37], v[2:3], v[38:39]
	v_add_co_u32_e32 v38, vcc, s3, v74
	v_cvt_pk_bf16_f32 v34, v34, v35
	v_cvt_pk_bf16_f32 v35, v44, v45
	v_cvt_pk_bf16_f32 v36, v36, v37
	v_cvt_pk_bf16_f32 v37, v40, v41
	v_addc_co_u32_e32 v39, vcc, 0, v75, vcc
	global_store_dwordx4 v[38:39], v[34:37], off sc1
	s_waitcnt vmcnt(9)
	v_lshlrev_b32_e32 v38, 16, v26
	v_and_b32_e32 v39, 0xffff0000, v26
	v_lshlrev_b32_e32 v34, 16, v30
	v_and_b32_e32 v35, 0xffff0000, v30
	v_lshlrev_b32_e32 v30, 16, v31
	v_and_b32_e32 v31, 0xffff0000, v31
	v_lshlrev_b32_e32 v26, 16, v27
	v_and_b32_e32 v27, 0xffff0000, v27
	v_lshlrev_b32_e32 v36, 16, v32
	v_and_b32_e32 v37, 0xffff0000, v32
	v_lshlrev_b32_e32 v32, 16, v33
	v_and_b32_e32 v33, 0xffff0000, v33
	v_lshlrev_b32_e32 v40, 16, v28
	v_and_b32_e32 v41, 0xffff0000, v28
	v_lshlrev_b32_e32 v28, 16, v29
	v_and_b32_e32 v29, 0xffff0000, v29
	v_pk_fma_f32 v[34:35], v[236:237], v[38:39], v[34:35] neg_lo:[1,0,0] neg_hi:[1,0,0]
	v_pk_fma_f32 v[26:27], v[66:67], v[26:27], v[30:31]
	v_pk_fma_f32 v[30:31], v[236:237], v[40:41], v[36:37] neg_lo:[1,0,0] neg_hi:[1,0,0]
	v_pk_fma_f32 v[28:29], v[66:67], v[28:29], v[32:33]
	v_pk_mul_f32 v[32:33], v[26:27], v[26:27]
	v_pk_mul_f32 v[36:37], v[34:35], v[34:35]
	s_nop 0
	v_pk_mov_b32 v[38:39], v[36:37], v[32:33] op_sel:[1,0]
	v_mov_b32_e32 v37, v33
	v_pk_add_f32 v[32:33], v[38:39], v[36:37]
	v_pk_mul_f32 v[36:37], v[28:29], v[28:29]
	v_pk_mul_f32 v[38:39], v[30:31], v[30:31]
	v_mov_b32_e32 v40, v36
	v_mov_b32_e32 v41, v38
	v_mov_b32_e32 v38, v37
	v_pk_add_f32 v[36:37], v[40:41], v[38:39]
	v_add_f32_e32 v32, v32, v33
	v_add_f32_e32 v32, v37, v32
	v_add_f32_e32 v32, v36, v32
	ds_bpermute_b32 v33, v78, v32
	s_waitcnt lgkmcnt(0)
	v_add_f32_e32 v32, v32, v33
	ds_bpermute_b32 v33, v77, v32
	s_waitcnt lgkmcnt(0)
	v_add_f32_e32 v32, v32, v33
	ds_bpermute_b32 v33, v76, v32
	s_waitcnt lgkmcnt(0)
	v_add_f32_e32 v32, v32, v33
	ds_bpermute_b32 v33, v0, v32
	s_waitcnt lgkmcnt(0)
; __device__ __forceinline__ u32x4 pack8(const f32x4 v0, const f32x4 v1) { u32x4 w; w.x = cvt_pk_bf16(v0[0], v0[1]); w.y = cvt_pk_bf16(v0[2], v0[3]); w.z = cvt_pk_bf16(v1[0], v1[1]); w.w = cvt_pk_bf16(v1[2], v1[3]); return w; }
; __device__ __forceinline__ void unpack8(const u32x4 w, f32x4& v0, f32x4& v1) { v0 = (f32x4){bf_lo(w.x), bf_hi(w.x), bf_lo(w.y), bf_hi(w.y)}; v1 = (f32x4){bf_lo(w.z), bf_hi(w.z), bf_lo(w.w), bf_hi(w.w)}; }
; __device__ __forceinline__ float shfl_xor_l(float v, int mask, int lane) { return __builtin_bit_cast(float, __builtin_amdgcn_ds_bpermute((lane ^ mask) << 2, __builtin_bit_cast(int, v))); }
; __global__ void __launch_bounds__(NWAVES * 64, 2) mk_fwd(Args a) {
;     ...
;                 for (int it = 0; it < 8; ++it) {
;                     f32x4 a0, a1, b0, b1; unpack8(va[it], a0, a1); unpack8(vb[it], b0, b1);
;                     const f32x4 d0 = a0 - b0 * lam, d1 = a1 - b1 * lam;
;                     float ss = (d0[0] * d0[0] + d0[1] * d0[1]) + (d0[2] * d0[2] + d0[3] * d0[3]) + (d1[0] * d1[0] + d1[1] * d1[1]) + (d1[2] * d1[2] + d1[3] * d1[3]);
;                     ss += pg8::shfl_xor_l(ss, 1, ln); ss += pg8::shfl_xor_l(ss, 2, ln); ss += pg8::shfl_xor_l(ss, 4, ln); ss += pg8::shfl_xor_l(ss, 8, ln);
;                     const float rs = osc * __builtin_amdgcn_rsqf(ss * (1.0f / 128.0f) + 1e-6f);
;                     *(v4u*)(Qb + offc + (size_t)(4 * it) * DMOD) = pack8(d0 * rs * sw0, d1 * rs * sw1);
;                 }
	v_add_f32_e32 v32, v32, v33
	v_fmamk_f32 v32, v32, 0x3c000000, v245
	v_rsq_f32_e32 v32, v32
	s_nop 0
	v_mul_f32_e32 v32, v249, v32
	v_pk_mul_f32 v[34:35], v[34:35], v[32:33] op_sel_hi:[1,0]
	v_pk_mul_f32 v[26:27], v[26:27], v[32:33] op_sel_hi:[1,0]
	v_pk_mul_f32 v[30:31], v[30:31], v[32:33] op_sel_hi:[1,0]
	v_pk_mul_f32 v[28:29], v[28:29], v[32:33] op_sel_hi:[1,0]
	v_pk_mul_f32 v[36:37], v[8:9], v[26:27]
	v_pk_mul_f32 v[26:27], v[6:7], v[34:35]
	v_pk_mul_f32 v[32:33], v[4:5], v[28:29]
	v_pk_mul_f32 v[28:29], v[2:3], v[30:31]
	v_add_co_u32_e32 v30, vcc, s4, v74
	v_cvt_pk_bf16_f32 v26, v26, v27
	v_cvt_pk_bf16_f32 v27, v36, v37
	v_cvt_pk_bf16_f32 v28, v28, v29
	v_cvt_pk_bf16_f32 v29, v32, v33
	v_addc_co_u32_e32 v31, vcc, 0, v75, vcc
	global_store_dwordx4 v[30:31], v[26:29], off sc1
	s_waitcnt vmcnt(8)
	v_lshlrev_b32_e32 v30, 16, v18
	v_and_b32_e32 v31, 0xffff0000, v18
	v_lshlrev_b32_e32 v26, 16, v22
	v_and_b32_e32 v27, 0xffff0000, v22
	v_lshlrev_b32_e32 v22, 16, v23
	v_and_b32_e32 v23, 0xffff0000, v23
	v_lshlrev_b32_e32 v18, 16, v19
	v_and_b32_e32 v19, 0xffff0000, v19
	v_lshlrev_b32_e32 v28, 16, v24
	v_and_b32_e32 v29, 0xffff0000, v24
	v_lshlrev_b32_e32 v24, 16, v25
	v_and_b32_e32 v25, 0xffff0000, v25
	v_lshlrev_b32_e32 v32, 16, v20
	v_and_b32_e32 v33, 0xffff0000, v20
	v_lshlrev_b32_e32 v20, 16, v21
	v_and_b32_e32 v21, 0xffff0000, v21
	v_pk_fma_f32 v[26:27], v[236:237], v[30:31], v[26:27] neg_lo:[1,0,0] neg_hi:[1,0,0]
	v_pk_fma_f32 v[18:19], v[66:67], v[18:19], v[22:23]
	v_pk_fma_f32 v[22:23], v[236:237], v[32:33], v[28:29] neg_lo:[1,0,0] neg_hi:[1,0,0]
	v_pk_fma_f32 v[20:21], v[66:67], v[20:21], v[24:25]
	v_pk_mul_f32 v[24:25], v[18:19], v[18:19]
	v_pk_mul_f32 v[28:29], v[26:27], v[26:27]
	s_nop 0
	v_pk_mov_b32 v[30:31], v[28:29], v[24:25] op_sel:[1,0]
	v_mov_b32_e32 v29, v25
	v_pk_add_f32 v[24:25], v[30:31], v[28:29]
	v_pk_mul_f32 v[28:29], v[20:21], v[20:21]
	v_pk_mul_f32 v[30:31], v[22:23], v[22:23]
	v_mov_b32_e32 v32, v28
	v_mov_b32_e32 v33, v30
	v_mov_b32_e32 v30, v29
	v_pk_add_f32 v[28:29], v[32:33], v[30:31]
	v_add_f32_e32 v24, v24, v25
	v_add_f32_e32 v24, v29, v24
	v_add_f32_e32 v24, v28, v24
	ds_bpermute_b32 v25, v78, v24
	s_waitcnt lgkmcnt(0)
	v_add_f32_e32 v24, v24, v25
	ds_bpermute_b32 v25, v77, v24
	s_waitcnt lgkmcnt(0)
	v_add_f32_e32 v24, v24, v25
	ds_bpermute_b32 v25, v76, v24
	s_waitcnt lgkmcnt(0)
	v_add_f32_e32 v24, v24, v25
	ds_bpermute_b32 v25, v0, v24
	s_waitcnt lgkmcnt(0)
	v_add_f32_e32 v24, v24, v25
	v_fmamk_f32 v24, v24, 0x3c000000, v245
	v_rsq_f32_e32 v24, v24
	s_nop 0
	v_mul_f32_e32 v24, v249, v24
	v_pk_mul_f32 v[26:27], v[26:27], v[24:25] op_sel_hi:[1,0]
	v_pk_mul_f32 v[18:19], v[18:19], v[24:25] op_sel_hi:[1,0]
	v_pk_mul_f32 v[22:23], v[22:23], v[24:25] op_sel_hi:[1,0]
	v_pk_mul_f32 v[20:21], v[20:21], v[24:25] op_sel_hi:[1,0]
	v_pk_mul_f32 v[28:29], v[8:9], v[18:19]
	v_pk_mul_f32 v[18:19], v[6:7], v[26:27]
	v_pk_mul_f32 v[24:25], v[4:5], v[20:21]
	v_pk_mul_f32 v[20:21], v[2:3], v[22:23]
	v_add_co_u32_e32 v22, vcc, s12, v74
	v_cvt_pk_bf16_f32 v18, v18, v19
	v_cvt_pk_bf16_f32 v19, v28, v29
	v_cvt_pk_bf16_f32 v20, v20, v21
	v_cvt_pk_bf16_f32 v21, v24, v25
	v_addc_co_u32_e32 v23, vcc, 0, v75, vcc
	global_store_dwordx4 v[22:23], v[18:21], off sc1
	s_waitcnt vmcnt(7)
	v_lshlrev_b32_e32 v22, 16, v10
	v_and_b32_e32 v23, 0xffff0000, v10
	v_lshlrev_b32_e32 v18, 16, v14
	v_and_b32_e32 v19, 0xffff0000, v14
	v_lshlrev_b32_e32 v14, 16, v15
	v_and_b32_e32 v15, 0xffff0000, v15
	v_lshlrev_b32_e32 v10, 16, v11
	v_and_b32_e32 v11, 0xffff0000, v11
	v_lshlrev_b32_e32 v20, 16, v16
	v_and_b32_e32 v21, 0xffff0000, v16
	v_lshlrev_b32_e32 v16, 16, v17
	v_and_b32_e32 v17, 0xffff0000, v17
	v_lshlrev_b32_e32 v24, 16, v12
	v_and_b32_e32 v25, 0xffff0000, v12
	v_lshlrev_b32_e32 v12, 16, v13
	v_and_b32_e32 v13, 0xffff0000, v13
	v_pk_fma_f32 v[18:19], v[236:237], v[22:23], v[18:19] neg_lo:[1,0,0] neg_hi:[1,0,0]
	v_pk_fma_f32 v[10:11], v[66:67], v[10:11], v[14:15]
	v_pk_fma_f32 v[14:15], v[236:237], v[24:25], v[20:21] neg_lo:[1,0,0] neg_hi:[1,0,0]
	v_pk_fma_f32 v[12:13], v[66:67], v[12:13], v[16:17]
	v_pk_mul_f32 v[16:17], v[10:11], v[10:11]
	v_pk_mul_f32 v[20:21], v[18:19], v[18:19]
	s_nop 0
	v_pk_mov_b32 v[22:23], v[20:21], v[16:17] op_sel:[1,0]
	v_mov_b32_e32 v21, v17
	v_pk_add_f32 v[16:17], v[22:23], v[20:21]
	v_pk_mul_f32 v[20:21], v[12:13], v[12:13]
	v_pk_mul_f32 v[22:23], v[14:15], v[14:15]
	v_mov_b32_e32 v24, v20
	v_mov_b32_e32 v25, v22
	v_mov_b32_e32 v22, v21
	v_pk_add_f32 v[20:21], v[24:25], v[22:23]
	v_add_f32_e32 v16, v16, v17
	v_add_f32_e32 v16, v21, v16
	v_add_f32_e32 v16, v20, v16
	ds_bpermute_b32 v17, v78, v16
	s_waitcnt lgkmcnt(0)
	v_add_f32_e32 v16, v16, v17
	ds_bpermute_b32 v17, v77, v16
	s_waitcnt lgkmcnt(0)
	v_add_f32_e32 v16, v16, v17
	ds_bpermute_b32 v17, v76, v16
	s_waitcnt lgkmcnt(0)
	v_add_f32_e32 v16, v16, v17
	ds_bpermute_b32 v0, v0, v16
	s_waitcnt lgkmcnt(0)
	v_add_f32_e32 v0, v16, v0
	v_fmamk_f32 v0, v0, 0x3c000000, v245
	v_rsq_f32_e32 v0, v0
	s_nop 0
	v_mul_f32_e32 v0, v249, v0
	v_pk_mul_f32 v[16:17], v[18:19], v[0:1] op_sel_hi:[1,0]
	v_pk_mul_f32 v[10:11], v[10:11], v[0:1] op_sel_hi:[1,0]
	v_pk_mul_f32 v[6:7], v[6:7], v[16:17]
	v_pk_mul_f32 v[8:9], v[8:9], v[10:11]
	v_pk_mul_f32 v[10:11], v[14:15], v[0:1] op_sel_hi:[1,0]
	v_pk_mul_f32 v[12:13], v[12:13], v[0:1] op_sel_hi:[1,0]
	s_nop 0
	v_pk_mul_f32 v[12:13], v[4:5], v[12:13]
	v_pk_mul_f32 v[4:5], v[2:3], v[10:11]
	v_cvt_pk_bf16_f32 v2, v6, v7
	v_add_co_u32_e32 v6, vcc, 0xe000, v74
	v_cvt_pk_bf16_f32 v3, v8, v9
	v_cvt_pk_bf16_f32 v4, v4, v5
	v_cvt_pk_bf16_f32 v5, v12, v13
	v_addc_co_u32_e32 v7, vcc, 0, v75, vcc
	global_store_dwordx4 v[6:7], v[2:5], off sc1
	s_cbranch_scc1 .LBB0_343

; __device__ __forceinline__ void unpack8(const u32x4 w, f32x4& v0, f32x4& v1) { v0 = (f32x4){bf_lo(w.x), bf_hi(w.x), bf_lo(w.y), bf_hi(w.y)}; v1 = (f32x4){bf_lo(w.z), bf_hi(w.z), bf_lo(w.w), bf_hi(w.w)}; }
; __device__ __forceinline__ void conv_items(bf16u* BGb, const bf16u* CGb, const float* cw, int vcup, int G) {
;     ...
;     for (int item = vcup * 4 + qd; item < NTOK / 16; item += G * 4) {
;         const int r0 = item * 16;
;         f32x4 p2a = (f32x4){0.f, 0.f, 0.f, 0.f}, p2b = p2a, p1a = p2a, p1b = p2a;
;         if ((r0 & (SEQL - 1)) != 0) {
;             unpack8(*(const v4u*)(CGb + (size_t)(r0 - 2) * DMOD + c0), p2a, p2b);
;             unpack8(*(const v4u*)(CGb + (size_t)(r0 - 1) * DMOD + c0), p1a, p1b);
;         }
;         v4u pv[16], bv[16];
; #pragma unroll
;         for (int i = 0; i < 16; ++i) { const size_t off = (size_t)(r0 + i) * DMOD + c0; pv[i] = *(const v4u*)(CGb + off); bv[i] = *(const v4u*)(BGb + off); }
.LBB0_254:
	s_or_b64 exec, exec, s[40:41]
	v_add_u32_e32 v26, -15, v150
	v_ashrrev_i32_e32 v27, 31, v26
	v_lshlrev_b64 v[198:199], 11, v[26:27]
	v_or_b32_e32 v26, v198, v0
	v_mov_b32_e32 v27, v199
	v_lshl_add_u64 v[28:29], s[30:31], 0, v[26:27]
	v_lshl_add_u64 v[26:27], s[28:29], 0, v[26:27]
	global_load_dwordx4 v[202:205], v[28:29], off
	global_load_dwordx4 v[206:209], v[26:27], off
	v_add_u32_e32 v26, -14, v150
	v_ashrrev_i32_e32 v27, 31, v26
	v_lshlrev_b64 v[190:191], 11, v[26:27]
	v_or_b32_e32 v26, v190, v0
	v_mov_b32_e32 v27, v191
	v_lshl_add_u64 v[28:29], s[30:31], 0, v[26:27]
	v_lshl_add_u64 v[26:27], s[28:29], 0, v[26:27]
	global_load_dwordx4 v[142:145], v[28:29], off
	global_load_dwordx4 v[138:141], v[26:27], off
	v_add_u32_e32 v26, -13, v150
	v_ashrrev_i32_e32 v27, 31, v26
	v_lshlrev_b64 v[180:181], 11, v[26:27]
	v_or_b32_e32 v26, v180, v0
	v_mov_b32_e32 v27, v181
	v_lshl_add_u64 v[28:29], s[30:31], 0, v[26:27]
	v_lshl_add_u64 v[26:27], s[28:29], 0, v[26:27]
	global_load_dwordx4 v[134:137], v[28:29], off
	global_load_dwordx4 v[130:133], v[26:27], off
	v_add_u32_e32 v26, -12, v150
	v_ashrrev_i32_e32 v27, 31, v26
	v_lshlrev_b64 v[176:177], 11, v[26:27]
	v_or_b32_e32 v26, v176, v0
	v_mov_b32_e32 v27, v177
	v_lshl_add_u64 v[28:29], s[30:31], 0, v[26:27]
	v_lshl_add_u64 v[26:27], s[28:29], 0, v[26:27]
	global_load_dwordx4 v[126:129], v[28:29], off
	global_load_dwordx4 v[122:125], v[26:27], off
	v_add_u32_e32 v26, -11, v150
	v_ashrrev_i32_e32 v27, 31, v26
	v_lshlrev_b64 v[174:175], 11, v[26:27]
	v_or_b32_e32 v26, v174, v0
	v_mov_b32_e32 v27, v175
	v_lshl_add_u64 v[28:29], s[30:31], 0, v[26:27]
	v_lshl_add_u64 v[26:27], s[28:29], 0, v[26:27]
	global_load_dwordx4 v[118:121], v[28:29], off
	global_load_dwordx4 v[114:117], v[26:27], off
	v_add_u32_e32 v26, -10, v150
	v_ashrrev_i32_e32 v27, 31, v26
	v_lshlrev_b64 v[172:173], 11, v[26:27]
	v_or_b32_e32 v26, v172, v0
	v_mov_b32_e32 v27, v173
	v_lshl_add_u64 v[28:29], s[30:31], 0, v[26:27]
	v_lshl_add_u64 v[26:27], s[28:29], 0, v[26:27]
	global_load_dwordx4 v[110:113], v[28:29], off
	global_load_dwordx4 v[106:109], v[26:27], off
	v_add_u32_e32 v26, -9, v150
	v_ashrrev_i32_e32 v27, 31, v26
	v_lshlrev_b64 v[170:171], 11, v[26:27]
	v_or_b32_e32 v26, v170, v0
	v_mov_b32_e32 v27, v171
	v_lshl_add_u64 v[28:29], s[30:31], 0, v[26:27]
	v_lshl_add_u64 v[26:27], s[28:29], 0, v[26:27]
	global_load_dwordx4 v[102:105], v[28:29], off
	global_load_dwordx4 v[98:101], v[26:27], off
	v_add_u32_e32 v26, -8, v150
	v_ashrrev_i32_e32 v27, 31, v26
	v_lshlrev_b64 v[168:169], 11, v[26:27]
	v_or_b32_e32 v26, v168, v0
	v_mov_b32_e32 v27, v169
	v_lshl_add_u64 v[28:29], s[30:31], 0, v[26:27]
	v_lshl_add_u64 v[26:27], s[28:29], 0, v[26:27]
	global_load_dwordx4 v[94:97], v[28:29], off
	global_load_dwordx4 v[90:93], v[26:27], off
	v_add_u32_e32 v26, -7, v150
	v_ashrrev_i32_e32 v27, 31, v26
	v_lshlrev_b64 v[166:167], 11, v[26:27]
	v_or_b32_e32 v26, v166, v0
	v_mov_b32_e32 v27, v167
	v_lshl_add_u64 v[28:29], s[30:31], 0, v[26:27]
	v_lshl_add_u64 v[26:27], s[28:29], 0, v[26:27]
	global_load_dwordx4 v[86:89], v[28:29], off
	global_load_dwordx4 v[82:85], v[26:27], off
	v_add_u32_e32 v26, -6, v150
	v_ashrrev_i32_e32 v27, 31, v26
	v_lshlrev_b64 v[164:165], 11, v[26:27]
	v_or_b32_e32 v26, v164, v0
	v_mov_b32_e32 v27, v165
	v_lshl_add_u64 v[28:29], s[30:31], 0, v[26:27]
	v_lshl_add_u64 v[26:27], s[28:29], 0, v[26:27]
	global_load_dwordx4 v[78:81], v[28:29], off
	global_load_dwordx4 v[74:77], v[26:27], off
	v_add_u32_e32 v26, -5, v150
	v_ashrrev_i32_e32 v27, 31, v26
	v_lshlrev_b64 v[162:163], 11, v[26:27]
	v_or_b32_e32 v26, v162, v0
	v_mov_b32_e32 v27, v163
	v_lshl_add_u64 v[28:29], s[30:31], 0, v[26:27]
	v_lshl_add_u64 v[26:27], s[28:29], 0, v[26:27]
	global_load_dwordx4 v[70:73], v[28:29], off
	global_load_dwordx4 v[66:69], v[26:27], off
	v_add_u32_e32 v26, -4, v150
	v_ashrrev_i32_e32 v27, 31, v26
	v_lshlrev_b64 v[160:161], 11, v[26:27]
	v_or_b32_e32 v26, v160, v0
	v_mov_b32_e32 v27, v161
	v_lshl_add_u64 v[28:29], s[30:31], 0, v[26:27]
	v_lshl_add_u64 v[26:27], s[28:29], 0, v[26:27]
	global_load_dwordx4 v[62:65], v[28:29], off
	global_load_dwordx4 v[58:61], v[26:27], off
	v_add_u32_e32 v26, -3, v150
	v_ashrrev_i32_e32 v27, 31, v26
	v_lshlrev_b64 v[158:159], 11, v[26:27]
	v_or_b32_e32 v26, v158, v0
	v_mov_b32_e32 v27, v159
	v_lshl_add_u64 v[28:29], s[30:31], 0, v[26:27]
	v_lshl_add_u64 v[26:27], s[28:29], 0, v[26:27]
	s_waitcnt vmcnt(27)
	v_pk_mul_f32 v[214:215], v[10:11], v[186:187]
	global_load_dwordx4 v[54:57], v[28:29], off
	global_load_dwordx4 v[50:53], v[26:27], off
	v_add_u32_e32 v26, -2, v150
	s_waitcnt vmcnt(25)
	v_lshlrev_b32_e32 v210, 16, v202
	v_and_b32_e32 v211, 0xffff0000, v202
	v_pk_fma_f32 v[196:197], v[6:7], v[196:197], v[214:215]
	v_ashrrev_i32_e32 v27, 31, v26
	s_waitcnt vmcnt(24)
; __device__ __forceinline__ u32x4 pack8(const f32x4 v0, const f32x4 v1) { u32x4 w; w.x = cvt_pk_bf16(v0[0], v0[1]); w.y = cvt_pk_bf16(v0[2], v0[3]); w.z = cvt_pk_bf16(v1[0], v1[1]); w.w = cvt_pk_bf16(v1[2], v1[3]); return w; }
; __device__ __forceinline__ void unpack8(const u32x4 w, f32x4& v0, f32x4& v1) { v0 = (f32x4){bf_lo(w.x), bf_hi(w.x), bf_lo(w.y), bf_hi(w.y)}; v1 = (f32x4){bf_lo(w.z), bf_hi(w.z), bf_lo(w.w), bf_hi(w.w)}; }
; __device__ __forceinline__ void conv_items(bf16u* BGb, const bf16u* CGb, const float* cw, int vcup, int G) {
;     ...
;         for (int i = 0; i < 16; ++i) { const size_t off = (size_t)(r0 + i) * DMOD + c0; pv[i] = *(const v4u*)(CGb + off); bv[i] = *(const v4u*)(BGb + off); }
; #pragma unroll
;         for (int i = 0; i < 16; ++i) {
;             const size_t off = (size_t)(r0 + i) * DMOD + c0;
;             f32x4 p0a, p0b, ba, bb;
;             unpack8(pv[i], p0a, p0b); unpack8(bv[i], ba, bb);
;             f32x4 ya, yb;
; #pragma unroll
;             for (int e = 0; e < 4; ++e) { ya[e] = ba[e] * (w0[e] * p2a[e] + w1[e] * p1a[e] + w2[e] * p0a[e]); yb[e] = bb[e] * (w0[4 + e] * p2b[e] + w1[4 + e] * p1b[e] + w2[4 + e] * p0b[e]); }
;             *(v4u*)(BGb + off) = pack8(ya, yb);
;             p2a = p1a; p2b = p1b; p1a = p0a; p1b = p0b;
;         }
	v_lshlrev_b32_e32 v212, 16, v206
	v_and_b32_e32 v213, 0xffff0000, v206
	v_pk_fma_f32 v[196:197], v[14:15], v[210:211], v[196:197]
	v_pk_mul_f32 v[216:217], v[18:19], v[184:185]
	v_lshlrev_b64 v[156:157], 11, v[26:27]
	v_pk_mul_f32 v[196:197], v[196:197], v[212:213]
	v_lshlrev_b32_e32 v212, 16, v204
	v_and_b32_e32 v213, 0xffff0000, v204
	v_pk_fma_f32 v[194:195], v[2:3], v[194:195], v[216:217]
	v_or_b32_e32 v26, v156, v0
	v_mov_b32_e32 v27, v157
	v_lshlrev_b32_e32 v214, 16, v208
	v_and_b32_e32 v215, 0xffff0000, v208
	v_pk_fma_f32 v[194:195], v[22:23], v[212:213], v[194:195]
	v_lshl_add_u64 v[28:29], s[30:31], 0, v[26:27]
	v_lshl_add_u64 v[26:27], s[28:29], 0, v[26:27]
	v_pk_mul_f32 v[194:195], v[194:195], v[214:215]
	v_pk_mul_f32 v[214:215], v[12:13], v[182:183]
	global_load_dwordx4 v[46:49], v[28:29], off
	global_load_dwordx4 v[42:45], v[26:27], off
	v_add_u32_e32 v26, -1, v150
	v_lshlrev_b32_e32 v202, 16, v203
	v_and_b32_e32 v203, 0xffff0000, v203
	v_pk_fma_f32 v[192:193], v[8:9], v[192:193], v[214:215]
	v_ashrrev_i32_e32 v27, 31, v26
	v_lshlrev_b32_e32 v206, 16, v207
	v_and_b32_e32 v207, 0xffff0000, v207
	v_pk_fma_f32 v[192:193], v[16:17], v[202:203], v[192:193]
	v_lshlrev_b64 v[154:155], 11, v[26:27]
	v_pk_mul_f32 v[206:207], v[192:193], v[206:207]
	v_lshlrev_b32_e32 v192, 16, v209
	v_and_b32_e32 v193, 0xffff0000, v209
	v_pk_mul_f32 v[208:209], v[20:21], v[178:179]
	v_or_b32_e32 v26, v154, v0
	v_mov_b32_e32 v27, v155
	v_ashrrev_i32_e32 v151, 31, v150
	v_lshlrev_b32_e32 v204, 16, v205
	v_and_b32_e32 v205, 0xffff0000, v205
	v_pk_fma_f32 v[188:189], v[4:5], v[188:189], v[208:209]
	v_lshl_add_u64 v[28:29], s[30:31], 0, v[26:27]
	v_lshl_add_u64 v[26:27], s[28:29], 0, v[26:27]
	v_lshlrev_b64 v[152:153], 11, v[150:151]
	v_pk_fma_f32 v[188:189], v[24:25], v[204:205], v[188:189]
	global_load_dwordx4 v[38:41], v[28:29], off
	global_load_dwordx4 v[34:37], v[26:27], off
	v_or_b32_e32 v26, v152, v0
	v_mov_b32_e32 v27, v153
	v_pk_mul_f32 v[188:189], v[188:189], v[192:193]
	v_lshl_add_u64 v[28:29], s[30:31], 0, v[26:27]
	v_lshl_add_u64 v[26:27], s[28:29], 0, v[26:27]
	v_cvt_pk_bf16_f32 v192, v196, v197
	v_cvt_pk_bf16_f32 v193, v206, v207
	v_cvt_pk_bf16_f32 v194, v194, v195
	v_cvt_pk_bf16_f32 v195, v188, v189
	v_lshl_add_u64 v[188:189], v[148:149], 0, v[198:199]
	global_load_dwordx4 v[30:33], v[28:29], off
	s_nop 0
	global_load_dwordx4 v[26:29], v[26:27], off
	v_pk_mul_f32 v[196:197], v[18:19], v[212:213]
	global_store_dwordx4 v[188:189], v[192:195], off sc1
	s_waitcnt vmcnt(30)
	v_lshlrev_b32_e32 v188, 16, v142
	v_and_b32_e32 v189, 0xffff0000, v142
	v_pk_mul_f32 v[194:195], v[10:11], v[210:211]
	s_waitcnt vmcnt(29)
	v_lshlrev_b32_e32 v192, 16, v138
	v_pk_fma_f32 v[186:187], v[6:7], v[186:187], v[194:195]
	v_and_b32_e32 v193, 0xffff0000, v138
	v_pk_fma_f32 v[186:187], v[14:15], v[188:189], v[186:187]
	v_pk_fma_f32 v[184:185], v[2:3], v[184:185], v[196:197]
	v_pk_mul_f32 v[186:187], v[186:187], v[192:193]
	v_lshlrev_b32_e32 v192, 16, v144
	v_and_b32_e32 v193, 0xffff0000, v144
	v_lshlrev_b32_e32 v194, 16, v140
	v_and_b32_e32 v195, 0xffff0000, v140
	v_pk_fma_f32 v[184:185], v[22:23], v[192:193], v[184:185]
	v_lshlrev_b32_e32 v142, 16, v143
	v_pk_mul_f32 v[184:185], v[184:185], v[194:195]
	v_pk_mul_f32 v[194:195], v[12:13], v[202:203]
	v_and_b32_e32 v143, 0xffff0000, v143
	v_pk_fma_f32 v[182:183], v[8:9], v[182:183], v[194:195]
	v_lshlrev_b32_e32 v138, 16, v139
	v_and_b32_e32 v139, 0xffff0000, v139
	v_pk_fma_f32 v[182:183], v[16:17], v[142:143], v[182:183]
	v_lshlrev_b32_e32 v144, 16, v145
	v_pk_mul_f32 v[182:183], v[182:183], v[138:139]
	v_lshlrev_b32_e32 v138, 16, v141
	v_and_b32_e32 v139, 0xffff0000, v141
	v_pk_mul_f32 v[140:141], v[20:21], v[204:205]
	v_and_b32_e32 v145, 0xffff0000, v145
	v_pk_fma_f32 v[140:141], v[4:5], v[178:179], v[140:141]
	v_add_u32_e32 v200, s89, v200
	v_pk_fma_f32 v[140:141], v[24:25], v[144:145], v[140:141]
	v_cmp_lt_i32_e32 vcc, s10, v200
	v_pk_mul_f32 v[178:179], v[140:141], v[138:139]
	v_cvt_pk_bf16_f32 v138, v186, v187
	v_cvt_pk_bf16_f32 v139, v182, v183
	v_cvt_pk_bf16_f32 v140, v184, v185
	v_cvt_pk_bf16_f32 v141, v178, v179
	v_lshl_add_u64 v[178:179], v[148:149], 0, v[190:191]
	global_store_dwordx4 v[178:179], v[138:141], off sc1
	v_pk_mul_f32 v[178:179], v[10:11], v[188:189]
	v_pk_mul_f32 v[184:185], v[18:19], v[192:193]
	s_waitcnt vmcnt(29)
	v_lshlrev_b32_e32 v138, 16, v134
	v_and_b32_e32 v139, 0xffff0000, v134
	v_pk_fma_f32 v[178:179], v[6:7], v[210:211], v[178:179]
	s_waitcnt vmcnt(28)
	v_lshlrev_b32_e32 v140, 16, v130
	v_and_b32_e32 v141, 0xffff0000, v130
	v_pk_fma_f32 v[178:179], v[14:15], v[138:139], v[178:179]
	v_pk_fma_f32 v[184:185], v[2:3], v[212:213], v[184:185]
	v_pk_mul_f32 v[140:141], v[178:179], v[140:141]
	v_lshlrev_b32_e32 v178, 16, v136
	v_and_b32_e32 v179, 0xffff0000, v136
	v_lshlrev_b32_e32 v182, 16, v132
	v_and_b32_e32 v183, 0xffff0000, v132
	v_pk_fma_f32 v[184:185], v[22:23], v[178:179], v[184:185]
	v_lshlrev_b32_e32 v134, 16, v135
	v_pk_mul_f32 v[182:183], v[184:185], v[182:183]
	v_pk_mul_f32 v[184:185], v[12:13], v[142:143]
	v_and_b32_e32 v135, 0xffff0000, v135
	v_pk_fma_f32 v[184:185], v[8:9], v[202:203], v[184:185]
	v_lshlrev_b32_e32 v130, 16, v131
	v_and_b32_e32 v131, 0xffff0000, v131
	v_pk_fma_f32 v[184:185], v[16:17], v[134:135], v[184:185]
	v_lshlrev_b32_e32 v136, 16, v137
	v_pk_mul_f32 v[184:185], v[184:185], v[130:131]
	v_lshlrev_b32_e32 v130, 16, v133
	v_and_b32_e32 v131, 0xffff0000, v133
	v_pk_mul_f32 v[132:133], v[20:21], v[144:145]
	v_and_b32_e32 v137, 0xffff0000, v137
	v_pk_fma_f32 v[132:133], v[4:5], v[204:205], v[132:133]
	s_or_b64 s[38:39], vcc, s[38:39]
	v_pk_fma_f32 v[132:133], v[24:25], v[136:137], v[132:133]
	v_add_u32_e32 v150, s44, v150
	v_pk_mul_f32 v[186:187], v[132:133], v[130:131]
	v_cvt_pk_bf16_f32 v130, v140, v141
	v_cvt_pk_bf16_f32 v131, v184, v185
	v_cvt_pk_bf16_f32 v132, v182, v183
	v_cvt_pk_bf16_f32 v133, v186, v187
	v_lshl_add_u64 v[140:141], v[148:149], 0, v[180:181]
	global_store_dwordx4 v[140:141], v[130:133], off sc1
	v_pk_mul_f32 v[140:141], v[10:11], v[138:139]
	v_pk_mul_f32 v[182:183], v[18:19], v[178:179]
	s_waitcnt vmcnt(28)
; __device__ __forceinline__ u32x4 pack8(const f32x4 v0, const f32x4 v1) { u32x4 w; w.x = cvt_pk_bf16(v0[0], v0[1]); w.y = cvt_pk_bf16(v0[2], v0[3]); w.z = cvt_pk_bf16(v1[0], v1[1]); w.w = cvt_pk_bf16(v1[2], v1[3]); return w; }
; __device__ __forceinline__ void unpack8(const u32x4 w, f32x4& v0, f32x4& v1) { v0 = (f32x4){bf_lo(w.x), bf_hi(w.x), bf_lo(w.y), bf_hi(w.y)}; v1 = (f32x4){bf_lo(w.z), bf_hi(w.z), bf_lo(w.w), bf_hi(w.w)}; }
; __device__ __forceinline__ void conv_items(bf16u* BGb, const bf16u* CGb, const float* cw, int vcup, int G) {
;     ...
;         for (int i = 0; i < 16; ++i) {
;             const size_t off = (size_t)(r0 + i) * DMOD + c0;
;             f32x4 p0a, p0b, ba, bb;
;             unpack8(pv[i], p0a, p0b); unpack8(bv[i], ba, bb);
;             f32x4 ya, yb;
; #pragma unroll
;             for (int e = 0; e < 4; ++e) { ya[e] = ba[e] * (w0[e] * p2a[e] + w1[e] * p1a[e] + w2[e] * p0a[e]); yb[e] = bb[e] * (w0[4 + e] * p2b[e] + w1[4 + e] * p1b[e] + w2[4 + e] * p0b[e]); }
;             *(v4u*)(BGb + off) = pack8(ya, yb);
;             p2a = p1a; p2b = p1b; p1a = p0a; p1b = p0b;
;         }
	v_lshlrev_b32_e32 v130, 16, v126
	v_and_b32_e32 v131, 0xffff0000, v126
	v_pk_fma_f32 v[140:141], v[6:7], v[188:189], v[140:141]
	s_waitcnt vmcnt(27)
	v_lshlrev_b32_e32 v132, 16, v122
	v_and_b32_e32 v133, 0xffff0000, v122
	v_pk_fma_f32 v[140:141], v[14:15], v[130:131], v[140:141]
	v_pk_fma_f32 v[182:183], v[2:3], v[192:193], v[182:183]
	v_pk_mul_f32 v[132:133], v[140:141], v[132:133]
	v_lshlrev_b32_e32 v140, 16, v128
	v_and_b32_e32 v141, 0xffff0000, v128
	v_lshlrev_b32_e32 v180, 16, v124
	v_and_b32_e32 v181, 0xffff0000, v124
	v_pk_fma_f32 v[182:183], v[22:23], v[140:141], v[182:183]
	v_lshlrev_b32_e32 v126, 16, v127
	v_pk_mul_f32 v[180:181], v[182:183], v[180:181]
	v_pk_mul_f32 v[182:183], v[12:13], v[134:135]
	v_and_b32_e32 v127, 0xffff0000, v127
	v_pk_fma_f32 v[142:143], v[8:9], v[142:143], v[182:183]
	v_lshlrev_b32_e32 v122, 16, v123
	v_and_b32_e32 v123, 0xffff0000, v123
	v_pk_fma_f32 v[142:143], v[16:17], v[126:127], v[142:143]
	v_lshlrev_b32_e32 v128, 16, v129
	v_pk_mul_f32 v[142:143], v[142:143], v[122:123]
	v_lshlrev_b32_e32 v122, 16, v125
	v_and_b32_e32 v123, 0xffff0000, v125
	v_pk_mul_f32 v[124:125], v[20:21], v[136:137]
	v_and_b32_e32 v129, 0xffff0000, v129
	v_pk_fma_f32 v[124:125], v[4:5], v[144:145], v[124:125]
	s_nop 0
	v_pk_fma_f32 v[124:125], v[24:25], v[128:129], v[124:125]
	s_nop 0
	v_pk_mul_f32 v[144:145], v[124:125], v[122:123]
	v_cvt_pk_bf16_f32 v122, v132, v133
	v_cvt_pk_bf16_f32 v123, v142, v143
	v_cvt_pk_bf16_f32 v124, v180, v181
	v_cvt_pk_bf16_f32 v125, v144, v145
	v_lshl_add_u64 v[132:133], v[148:149], 0, v[176:177]
	global_store_dwordx4 v[132:133], v[122:125], off sc1
	v_pk_mul_f32 v[132:133], v[10:11], v[130:131]
	v_pk_mul_f32 v[142:143], v[18:19], v[140:141]
	s_waitcnt vmcnt(27)
	v_lshlrev_b32_e32 v122, 16, v118
	v_and_b32_e32 v123, 0xffff0000, v118
	v_pk_fma_f32 v[132:133], v[6:7], v[138:139], v[132:133]
	s_waitcnt vmcnt(26)
	v_lshlrev_b32_e32 v124, 16, v114
	v_and_b32_e32 v125, 0xffff0000, v114
	v_pk_fma_f32 v[132:133], v[14:15], v[122:123], v[132:133]
	v_pk_fma_f32 v[142:143], v[2:3], v[178:179], v[142:143]
	v_pk_mul_f32 v[124:125], v[132:133], v[124:125]
	v_lshlrev_b32_e32 v132, 16, v120
	v_and_b32_e32 v133, 0xffff0000, v120
	v_lshlrev_b32_e32 v138, 16, v116
	v_and_b32_e32 v139, 0xffff0000, v116
	v_pk_fma_f32 v[142:143], v[22:23], v[132:133], v[142:143]
	v_lshlrev_b32_e32 v118, 16, v119
	v_pk_mul_f32 v[138:139], v[142:143], v[138:139]
	v_pk_mul_f32 v[142:143], v[12:13], v[126:127]
	v_and_b32_e32 v119, 0xffff0000, v119
	v_pk_fma_f32 v[134:135], v[8:9], v[134:135], v[142:143]
	v_lshlrev_b32_e32 v114, 16, v115
	v_and_b32_e32 v115, 0xffff0000, v115
	v_pk_fma_f32 v[134:135], v[16:17], v[118:119], v[134:135]
	v_lshlrev_b32_e32 v120, 16, v121
	v_pk_mul_f32 v[134:135], v[134:135], v[114:115]
	v_lshlrev_b32_e32 v114, 16, v117
	v_and_b32_e32 v115, 0xffff0000, v117
	v_pk_mul_f32 v[116:117], v[20:21], v[128:129]
	v_and_b32_e32 v121, 0xffff0000, v121
	v_pk_fma_f32 v[116:117], v[4:5], v[136:137], v[116:117]
	s_nop 0
	v_pk_fma_f32 v[116:117], v[24:25], v[120:121], v[116:117]
	s_nop 0
	v_pk_mul_f32 v[136:137], v[116:117], v[114:115]
	v_cvt_pk_bf16_f32 v114, v124, v125
	v_cvt_pk_bf16_f32 v115, v134, v135
	v_cvt_pk_bf16_f32 v116, v138, v139
	v_cvt_pk_bf16_f32 v117, v136, v137
	v_lshl_add_u64 v[124:125], v[148:149], 0, v[174:175]
	global_store_dwordx4 v[124:125], v[114:117], off sc1
	v_pk_mul_f32 v[124:125], v[10:11], v[122:123]
	v_pk_mul_f32 v[134:135], v[18:19], v[132:133]
	s_waitcnt vmcnt(26)
	v_lshlrev_b32_e32 v114, 16, v110
	v_and_b32_e32 v115, 0xffff0000, v110
	v_pk_fma_f32 v[124:125], v[6:7], v[130:131], v[124:125]
	s_waitcnt vmcnt(25)
	v_lshlrev_b32_e32 v116, 16, v106
	v_and_b32_e32 v117, 0xffff0000, v106
	v_pk_fma_f32 v[124:125], v[14:15], v[114:115], v[124:125]
	v_pk_fma_f32 v[134:135], v[2:3], v[140:141], v[134:135]
	v_pk_mul_f32 v[116:117], v[124:125], v[116:117]
	v_lshlrev_b32_e32 v124, 16, v112
	v_and_b32_e32 v125, 0xffff0000, v112
	v_lshlrev_b32_e32 v130, 16, v108
	v_and_b32_e32 v131, 0xffff0000, v108
	v_pk_fma_f32 v[134:135], v[22:23], v[124:125], v[134:135]
	v_lshlrev_b32_e32 v110, 16, v111
	v_pk_mul_f32 v[130:131], v[134:135], v[130:131]
	v_pk_mul_f32 v[134:135], v[12:13], v[118:119]
	v_and_b32_e32 v111, 0xffff0000, v111
	v_pk_fma_f32 v[126:127], v[8:9], v[126:127], v[134:135]
	v_lshlrev_b32_e32 v106, 16, v107
	v_and_b32_e32 v107, 0xffff0000, v107
	v_pk_fma_f32 v[126:127], v[16:17], v[110:111], v[126:127]
	v_lshlrev_b32_e32 v112, 16, v113
	v_pk_mul_f32 v[126:127], v[126:127], v[106:107]
	v_lshlrev_b32_e32 v106, 16, v109
	v_and_b32_e32 v107, 0xffff0000, v109
	v_pk_mul_f32 v[108:109], v[20:21], v[120:121]
	v_and_b32_e32 v113, 0xffff0000, v113
	v_pk_fma_f32 v[108:109], v[4:5], v[128:129], v[108:109]
	s_nop 0
	v_pk_fma_f32 v[108:109], v[24:25], v[112:113], v[108:109]
	s_nop 0
	v_pk_mul_f32 v[128:129], v[108:109], v[106:107]
	v_cvt_pk_bf16_f32 v106, v116, v117
	v_cvt_pk_bf16_f32 v107, v126, v127
	v_cvt_pk_bf16_f32 v108, v130, v131
	v_cvt_pk_bf16_f32 v109, v128, v129
	v_lshl_add_u64 v[116:117], v[148:149], 0, v[172:173]
	global_store_dwordx4 v[116:117], v[106:109], off sc1
	v_pk_mul_f32 v[116:117], v[10:11], v[114:115]
	v_pk_mul_f32 v[126:127], v[18:19], v[124:125]
	s_waitcnt vmcnt(25)
	v_lshlrev_b32_e32 v106, 16, v102
	v_and_b32_e32 v107, 0xffff0000, v102
	v_pk_fma_f32 v[116:117], v[6:7], v[122:123], v[116:117]
	s_waitcnt vmcnt(24)
; __device__ __forceinline__ u32x4 pack8(const f32x4 v0, const f32x4 v1) { u32x4 w; w.x = cvt_pk_bf16(v0[0], v0[1]); w.y = cvt_pk_bf16(v0[2], v0[3]); w.z = cvt_pk_bf16(v1[0], v1[1]); w.w = cvt_pk_bf16(v1[2], v1[3]); return w; }
; __device__ __forceinline__ void unpack8(const u32x4 w, f32x4& v0, f32x4& v1) { v0 = (f32x4){bf_lo(w.x), bf_hi(w.x), bf_lo(w.y), bf_hi(w.y)}; v1 = (f32x4){bf_lo(w.z), bf_hi(w.z), bf_lo(w.w), bf_hi(w.w)}; }
; __device__ __forceinline__ void conv_items(bf16u* BGb, const bf16u* CGb, const float* cw, int vcup, int G) {
;     ...
;         for (int i = 0; i < 16; ++i) {
;             const size_t off = (size_t)(r0 + i) * DMOD + c0;
;             f32x4 p0a, p0b, ba, bb;
;             unpack8(pv[i], p0a, p0b); unpack8(bv[i], ba, bb);
;             f32x4 ya, yb;
; #pragma unroll
;             for (int e = 0; e < 4; ++e) { ya[e] = ba[e] * (w0[e] * p2a[e] + w1[e] * p1a[e] + w2[e] * p0a[e]); yb[e] = bb[e] * (w0[4 + e] * p2b[e] + w1[4 + e] * p1b[e] + w2[4 + e] * p0b[e]); }
;             *(v4u*)(BGb + off) = pack8(ya, yb);
;             p2a = p1a; p2b = p1b; p1a = p0a; p1b = p0b;
;         }
	v_lshlrev_b32_e32 v108, 16, v98
	v_and_b32_e32 v109, 0xffff0000, v98
	v_pk_fma_f32 v[116:117], v[14:15], v[106:107], v[116:117]
	v_pk_fma_f32 v[126:127], v[2:3], v[132:133], v[126:127]
	v_pk_mul_f32 v[108:109], v[116:117], v[108:109]
	v_lshlrev_b32_e32 v116, 16, v104
	v_and_b32_e32 v117, 0xffff0000, v104
	v_lshlrev_b32_e32 v122, 16, v100
	v_and_b32_e32 v123, 0xffff0000, v100
	v_pk_fma_f32 v[126:127], v[22:23], v[116:117], v[126:127]
	v_lshlrev_b32_e32 v102, 16, v103
	v_pk_mul_f32 v[122:123], v[126:127], v[122:123]
	v_pk_mul_f32 v[126:127], v[12:13], v[110:111]
	v_and_b32_e32 v103, 0xffff0000, v103
	v_pk_fma_f32 v[118:119], v[8:9], v[118:119], v[126:127]
	v_lshlrev_b32_e32 v98, 16, v99
	v_and_b32_e32 v99, 0xffff0000, v99
	v_pk_fma_f32 v[118:119], v[16:17], v[102:103], v[118:119]
	v_lshlrev_b32_e32 v104, 16, v105
	v_pk_mul_f32 v[118:119], v[118:119], v[98:99]
	v_lshlrev_b32_e32 v98, 16, v101
	v_and_b32_e32 v99, 0xffff0000, v101
	v_pk_mul_f32 v[100:101], v[20:21], v[112:113]
	v_and_b32_e32 v105, 0xffff0000, v105
	v_pk_fma_f32 v[100:101], v[4:5], v[120:121], v[100:101]
	s_nop 0
	v_pk_fma_f32 v[100:101], v[24:25], v[104:105], v[100:101]
	s_nop 0
	v_pk_mul_f32 v[120:121], v[100:101], v[98:99]
	v_cvt_pk_bf16_f32 v98, v108, v109
	v_cvt_pk_bf16_f32 v99, v118, v119
	v_cvt_pk_bf16_f32 v100, v122, v123
	v_cvt_pk_bf16_f32 v101, v120, v121
	v_lshl_add_u64 v[108:109], v[148:149], 0, v[170:171]
	global_store_dwordx4 v[108:109], v[98:101], off sc1
	v_pk_mul_f32 v[108:109], v[10:11], v[106:107]
	v_pk_mul_f32 v[118:119], v[18:19], v[116:117]
	s_waitcnt vmcnt(24)
	v_lshlrev_b32_e32 v98, 16, v94
	v_and_b32_e32 v99, 0xffff0000, v94
	v_pk_fma_f32 v[108:109], v[6:7], v[114:115], v[108:109]
	s_waitcnt vmcnt(23)
	v_lshlrev_b32_e32 v100, 16, v90
	v_and_b32_e32 v101, 0xffff0000, v90
	v_pk_fma_f32 v[108:109], v[14:15], v[98:99], v[108:109]
	v_pk_fma_f32 v[118:119], v[2:3], v[124:125], v[118:119]
	v_pk_mul_f32 v[100:101], v[108:109], v[100:101]
	v_lshlrev_b32_e32 v108, 16, v96
	v_and_b32_e32 v109, 0xffff0000, v96
	v_lshlrev_b32_e32 v114, 16, v92
	v_and_b32_e32 v115, 0xffff0000, v92
	v_pk_fma_f32 v[118:119], v[22:23], v[108:109], v[118:119]
	v_lshlrev_b32_e32 v94, 16, v95
	v_pk_mul_f32 v[114:115], v[118:119], v[114:115]
	v_pk_mul_f32 v[118:119], v[12:13], v[102:103]
	v_and_b32_e32 v95, 0xffff0000, v95
	v_pk_fma_f32 v[110:111], v[8:9], v[110:111], v[118:119]
	v_lshlrev_b32_e32 v90, 16, v91
	v_and_b32_e32 v91, 0xffff0000, v91
	v_pk_fma_f32 v[110:111], v[16:17], v[94:95], v[110:111]
	v_lshlrev_b32_e32 v96, 16, v97
	v_pk_mul_f32 v[110:111], v[110:111], v[90:91]
	v_lshlrev_b32_e32 v90, 16, v93
	v_and_b32_e32 v91, 0xffff0000, v93
	v_pk_mul_f32 v[92:93], v[20:21], v[104:105]
	v_and_b32_e32 v97, 0xffff0000, v97
	v_pk_fma_f32 v[92:93], v[4:5], v[112:113], v[92:93]
	s_nop 0
	v_pk_fma_f32 v[92:93], v[24:25], v[96:97], v[92:93]
	s_nop 0
	v_pk_mul_f32 v[112:113], v[92:93], v[90:91]
	v_cvt_pk_bf16_f32 v90, v100, v101
	v_cvt_pk_bf16_f32 v91, v110, v111
	v_cvt_pk_bf16_f32 v92, v114, v115
	v_cvt_pk_bf16_f32 v93, v112, v113
	v_lshl_add_u64 v[100:101], v[148:149], 0, v[168:169]
	global_store_dwordx4 v[100:101], v[90:93], off sc1
	v_pk_mul_f32 v[100:101], v[10:11], v[98:99]
	v_pk_mul_f32 v[110:111], v[18:19], v[108:109]
	s_waitcnt vmcnt(23)
	v_lshlrev_b32_e32 v90, 16, v86
	v_and_b32_e32 v91, 0xffff0000, v86
	v_pk_fma_f32 v[100:101], v[6:7], v[106:107], v[100:101]
	s_waitcnt vmcnt(22)
	v_lshlrev_b32_e32 v92, 16, v82
	v_and_b32_e32 v93, 0xffff0000, v82
	v_pk_fma_f32 v[100:101], v[14:15], v[90:91], v[100:101]
	v_pk_fma_f32 v[110:111], v[2:3], v[116:117], v[110:111]
	v_pk_mul_f32 v[92:93], v[100:101], v[92:93]
	v_lshlrev_b32_e32 v100, 16, v88
	v_and_b32_e32 v101, 0xffff0000, v88
	v_lshlrev_b32_e32 v106, 16, v84
	v_and_b32_e32 v107, 0xffff0000, v84
	v_pk_fma_f32 v[110:111], v[22:23], v[100:101], v[110:111]
	v_lshlrev_b32_e32 v86, 16, v87
	v_pk_mul_f32 v[106:107], v[110:111], v[106:107]
	v_pk_mul_f32 v[110:111], v[12:13], v[94:95]
	v_and_b32_e32 v87, 0xffff0000, v87
	v_pk_fma_f32 v[102:103], v[8:9], v[102:103], v[110:111]
	v_lshlrev_b32_e32 v82, 16, v83
	v_and_b32_e32 v83, 0xffff0000, v83
	v_pk_fma_f32 v[102:103], v[16:17], v[86:87], v[102:103]
	v_lshlrev_b32_e32 v88, 16, v89
	v_pk_mul_f32 v[102:103], v[102:103], v[82:83]
	v_lshlrev_b32_e32 v82, 16, v85
	v_and_b32_e32 v83, 0xffff0000, v85
	v_pk_mul_f32 v[84:85], v[20:21], v[96:97]
	v_and_b32_e32 v89, 0xffff0000, v89
	v_pk_fma_f32 v[84:85], v[4:5], v[104:105], v[84:85]
	s_nop 0
	v_pk_fma_f32 v[84:85], v[24:25], v[88:89], v[84:85]
	s_nop 0
	v_pk_mul_f32 v[104:105], v[84:85], v[82:83]
	v_cvt_pk_bf16_f32 v82, v92, v93
	v_cvt_pk_bf16_f32 v83, v102, v103
	v_cvt_pk_bf16_f32 v84, v106, v107
	v_cvt_pk_bf16_f32 v85, v104, v105
	v_lshl_add_u64 v[92:93], v[148:149], 0, v[166:167]
	global_store_dwordx4 v[92:93], v[82:85], off sc1
	v_pk_mul_f32 v[92:93], v[10:11], v[90:91]
	v_pk_mul_f32 v[102:103], v[18:19], v[100:101]
	s_waitcnt vmcnt(22)
	v_lshlrev_b32_e32 v82, 16, v78
	v_and_b32_e32 v83, 0xffff0000, v78
	v_pk_fma_f32 v[92:93], v[6:7], v[98:99], v[92:93]
	s_waitcnt vmcnt(21)
; __device__ __forceinline__ u32x4 pack8(const f32x4 v0, const f32x4 v1) { u32x4 w; w.x = cvt_pk_bf16(v0[0], v0[1]); w.y = cvt_pk_bf16(v0[2], v0[3]); w.z = cvt_pk_bf16(v1[0], v1[1]); w.w = cvt_pk_bf16(v1[2], v1[3]); return w; }
; __device__ __forceinline__ void unpack8(const u32x4 w, f32x4& v0, f32x4& v1) { v0 = (f32x4){bf_lo(w.x), bf_hi(w.x), bf_lo(w.y), bf_hi(w.y)}; v1 = (f32x4){bf_lo(w.z), bf_hi(w.z), bf_lo(w.w), bf_hi(w.w)}; }
; __device__ __forceinline__ void conv_items(bf16u* BGb, const bf16u* CGb, const float* cw, int vcup, int G) {
;     ...
;         for (int i = 0; i < 16; ++i) {
;             const size_t off = (size_t)(r0 + i) * DMOD + c0;
;             f32x4 p0a, p0b, ba, bb;
;             unpack8(pv[i], p0a, p0b); unpack8(bv[i], ba, bb);
;             f32x4 ya, yb;
; #pragma unroll
;             for (int e = 0; e < 4; ++e) { ya[e] = ba[e] * (w0[e] * p2a[e] + w1[e] * p1a[e] + w2[e] * p0a[e]); yb[e] = bb[e] * (w0[4 + e] * p2b[e] + w1[4 + e] * p1b[e] + w2[4 + e] * p0b[e]); }
;             *(v4u*)(BGb + off) = pack8(ya, yb);
;             p2a = p1a; p2b = p1b; p1a = p0a; p1b = p0b;
;         }
	v_lshlrev_b32_e32 v84, 16, v74
	v_and_b32_e32 v85, 0xffff0000, v74
	v_pk_fma_f32 v[92:93], v[14:15], v[82:83], v[92:93]
	v_pk_fma_f32 v[102:103], v[2:3], v[108:109], v[102:103]
	v_pk_mul_f32 v[84:85], v[92:93], v[84:85]
	v_lshlrev_b32_e32 v92, 16, v80
	v_and_b32_e32 v93, 0xffff0000, v80
	v_lshlrev_b32_e32 v98, 16, v76
	v_and_b32_e32 v99, 0xffff0000, v76
	v_pk_fma_f32 v[102:103], v[22:23], v[92:93], v[102:103]
	v_lshlrev_b32_e32 v78, 16, v79
	v_pk_mul_f32 v[98:99], v[102:103], v[98:99]
	v_pk_mul_f32 v[102:103], v[12:13], v[86:87]
	v_and_b32_e32 v79, 0xffff0000, v79
	v_pk_fma_f32 v[94:95], v[8:9], v[94:95], v[102:103]
	v_lshlrev_b32_e32 v74, 16, v75
	v_and_b32_e32 v75, 0xffff0000, v75
	v_pk_fma_f32 v[94:95], v[16:17], v[78:79], v[94:95]
	v_lshlrev_b32_e32 v80, 16, v81
	v_pk_mul_f32 v[94:95], v[94:95], v[74:75]
	v_lshlrev_b32_e32 v74, 16, v77
	v_and_b32_e32 v75, 0xffff0000, v77
	v_pk_mul_f32 v[76:77], v[20:21], v[88:89]
	v_and_b32_e32 v81, 0xffff0000, v81
	v_pk_fma_f32 v[76:77], v[4:5], v[96:97], v[76:77]
	s_nop 0
	v_pk_fma_f32 v[76:77], v[24:25], v[80:81], v[76:77]
	s_nop 0
	v_pk_mul_f32 v[96:97], v[76:77], v[74:75]
	v_cvt_pk_bf16_f32 v74, v84, v85
	v_cvt_pk_bf16_f32 v75, v94, v95
	v_cvt_pk_bf16_f32 v76, v98, v99
	v_cvt_pk_bf16_f32 v77, v96, v97
	v_lshl_add_u64 v[84:85], v[148:149], 0, v[164:165]
	global_store_dwordx4 v[84:85], v[74:77], off sc1
	v_pk_mul_f32 v[84:85], v[10:11], v[82:83]
	v_pk_mul_f32 v[94:95], v[18:19], v[92:93]
	s_waitcnt vmcnt(21)
	v_lshlrev_b32_e32 v74, 16, v70
	v_and_b32_e32 v75, 0xffff0000, v70
	v_pk_fma_f32 v[84:85], v[6:7], v[90:91], v[84:85]
	s_waitcnt vmcnt(20)
	v_lshlrev_b32_e32 v76, 16, v66
	v_and_b32_e32 v77, 0xffff0000, v66
	v_pk_fma_f32 v[84:85], v[14:15], v[74:75], v[84:85]
	v_pk_fma_f32 v[94:95], v[2:3], v[100:101], v[94:95]
	v_pk_mul_f32 v[76:77], v[84:85], v[76:77]
	v_lshlrev_b32_e32 v84, 16, v72
	v_and_b32_e32 v85, 0xffff0000, v72
	v_lshlrev_b32_e32 v90, 16, v68
	v_and_b32_e32 v91, 0xffff0000, v68
	v_pk_fma_f32 v[94:95], v[22:23], v[84:85], v[94:95]
	v_lshlrev_b32_e32 v70, 16, v71
	v_pk_mul_f32 v[90:91], v[94:95], v[90:91]
	v_pk_mul_f32 v[94:95], v[12:13], v[78:79]
	v_and_b32_e32 v71, 0xffff0000, v71
	v_pk_fma_f32 v[86:87], v[8:9], v[86:87], v[94:95]
	v_lshlrev_b32_e32 v66, 16, v67
	v_and_b32_e32 v67, 0xffff0000, v67
	v_pk_fma_f32 v[86:87], v[16:17], v[70:71], v[86:87]
	v_lshlrev_b32_e32 v72, 16, v73
	v_pk_mul_f32 v[86:87], v[86:87], v[66:67]
	v_lshlrev_b32_e32 v66, 16, v69
	v_and_b32_e32 v67, 0xffff0000, v69
	v_pk_mul_f32 v[68:69], v[20:21], v[80:81]
	v_and_b32_e32 v73, 0xffff0000, v73
	v_pk_fma_f32 v[68:69], v[4:5], v[88:89], v[68:69]
	s_nop 0
	v_pk_fma_f32 v[68:69], v[24:25], v[72:73], v[68:69]
	s_nop 0
	v_pk_mul_f32 v[88:89], v[68:69], v[66:67]
	v_cvt_pk_bf16_f32 v66, v76, v77
	v_cvt_pk_bf16_f32 v67, v86, v87
	v_cvt_pk_bf16_f32 v68, v90, v91
	v_cvt_pk_bf16_f32 v69, v88, v89
	v_lshl_add_u64 v[76:77], v[148:149], 0, v[162:163]
	global_store_dwordx4 v[76:77], v[66:69], off sc1
	v_pk_mul_f32 v[76:77], v[10:11], v[74:75]
	v_pk_mul_f32 v[86:87], v[18:19], v[84:85]
	s_waitcnt vmcnt(20)
	v_lshlrev_b32_e32 v66, 16, v62
	v_and_b32_e32 v67, 0xffff0000, v62
	v_pk_fma_f32 v[76:77], v[6:7], v[82:83], v[76:77]
	s_waitcnt vmcnt(19)
	v_lshlrev_b32_e32 v68, 16, v58
	v_and_b32_e32 v69, 0xffff0000, v58
	v_pk_fma_f32 v[76:77], v[14:15], v[66:67], v[76:77]
	v_pk_fma_f32 v[86:87], v[2:3], v[92:93], v[86:87]
	v_pk_mul_f32 v[68:69], v[76:77], v[68:69]
	v_lshlrev_b32_e32 v76, 16, v64
	v_and_b32_e32 v77, 0xffff0000, v64
	v_lshlrev_b32_e32 v82, 16, v60
	v_and_b32_e32 v83, 0xffff0000, v60
	v_pk_fma_f32 v[86:87], v[22:23], v[76:77], v[86:87]
	v_lshlrev_b32_e32 v62, 16, v63
	v_pk_mul_f32 v[82:83], v[86:87], v[82:83]
	v_pk_mul_f32 v[86:87], v[12:13], v[70:71]
	v_and_b32_e32 v63, 0xffff0000, v63
	v_pk_fma_f32 v[78:79], v[8:9], v[78:79], v[86:87]
	v_lshlrev_b32_e32 v58, 16, v59
	v_and_b32_e32 v59, 0xffff0000, v59
	v_pk_fma_f32 v[78:79], v[16:17], v[62:63], v[78:79]
	v_lshlrev_b32_e32 v64, 16, v65
	v_pk_mul_f32 v[78:79], v[78:79], v[58:59]
	v_lshlrev_b32_e32 v58, 16, v61
	v_and_b32_e32 v59, 0xffff0000, v61
	v_pk_mul_f32 v[60:61], v[20:21], v[72:73]
	v_and_b32_e32 v65, 0xffff0000, v65
	v_pk_fma_f32 v[60:61], v[4:5], v[80:81], v[60:61]
	s_nop 0
	v_pk_fma_f32 v[60:61], v[24:25], v[64:65], v[60:61]
	s_nop 0
	v_pk_mul_f32 v[80:81], v[60:61], v[58:59]
	v_cvt_pk_bf16_f32 v58, v68, v69
	v_cvt_pk_bf16_f32 v59, v78, v79
	v_cvt_pk_bf16_f32 v60, v82, v83
	v_cvt_pk_bf16_f32 v61, v80, v81
	v_lshl_add_u64 v[68:69], v[148:149], 0, v[160:161]
	global_store_dwordx4 v[68:69], v[58:61], off sc1
	v_pk_mul_f32 v[68:69], v[10:11], v[66:67]
	v_pk_mul_f32 v[78:79], v[18:19], v[76:77]
	s_waitcnt vmcnt(19)
	v_lshlrev_b32_e32 v58, 16, v54
	v_and_b32_e32 v59, 0xffff0000, v54
	v_pk_fma_f32 v[68:69], v[6:7], v[74:75], v[68:69]
	s_waitcnt vmcnt(18)
; __device__ __forceinline__ u32x4 pack8(const f32x4 v0, const f32x4 v1) { u32x4 w; w.x = cvt_pk_bf16(v0[0], v0[1]); w.y = cvt_pk_bf16(v0[2], v0[3]); w.z = cvt_pk_bf16(v1[0], v1[1]); w.w = cvt_pk_bf16(v1[2], v1[3]); return w; }
; __device__ __forceinline__ void unpack8(const u32x4 w, f32x4& v0, f32x4& v1) { v0 = (f32x4){bf_lo(w.x), bf_hi(w.x), bf_lo(w.y), bf_hi(w.y)}; v1 = (f32x4){bf_lo(w.z), bf_hi(w.z), bf_lo(w.w), bf_hi(w.w)}; }
; __device__ __forceinline__ void conv_items(bf16u* BGb, const bf16u* CGb, const float* cw, int vcup, int G) {
;     ...
;         for (int i = 0; i < 16; ++i) {
;             const size_t off = (size_t)(r0 + i) * DMOD + c0;
;             f32x4 p0a, p0b, ba, bb;
;             unpack8(pv[i], p0a, p0b); unpack8(bv[i], ba, bb);
;             f32x4 ya, yb;
; #pragma unroll
;             for (int e = 0; e < 4; ++e) { ya[e] = ba[e] * (w0[e] * p2a[e] + w1[e] * p1a[e] + w2[e] * p0a[e]); yb[e] = bb[e] * (w0[4 + e] * p2b[e] + w1[4 + e] * p1b[e] + w2[4 + e] * p0b[e]); }
;             *(v4u*)(BGb + off) = pack8(ya, yb);
;             p2a = p1a; p2b = p1b; p1a = p0a; p1b = p0b;
;         }
	v_lshlrev_b32_e32 v60, 16, v50
	v_and_b32_e32 v61, 0xffff0000, v50
	v_pk_fma_f32 v[68:69], v[14:15], v[58:59], v[68:69]
	v_pk_fma_f32 v[78:79], v[2:3], v[84:85], v[78:79]
	v_pk_mul_f32 v[60:61], v[68:69], v[60:61]
	v_lshlrev_b32_e32 v68, 16, v56
	v_and_b32_e32 v69, 0xffff0000, v56
	v_lshlrev_b32_e32 v74, 16, v52
	v_and_b32_e32 v75, 0xffff0000, v52
	v_pk_fma_f32 v[78:79], v[22:23], v[68:69], v[78:79]
	v_lshlrev_b32_e32 v54, 16, v55
	v_pk_mul_f32 v[74:75], v[78:79], v[74:75]
	v_pk_mul_f32 v[78:79], v[12:13], v[62:63]
	v_and_b32_e32 v55, 0xffff0000, v55
	v_pk_fma_f32 v[70:71], v[8:9], v[70:71], v[78:79]
	v_lshlrev_b32_e32 v50, 16, v51
	v_and_b32_e32 v51, 0xffff0000, v51
	v_pk_fma_f32 v[70:71], v[16:17], v[54:55], v[70:71]
	v_lshlrev_b32_e32 v56, 16, v57
	v_pk_mul_f32 v[70:71], v[70:71], v[50:51]
	v_lshlrev_b32_e32 v50, 16, v53
	v_and_b32_e32 v51, 0xffff0000, v53
	v_pk_mul_f32 v[52:53], v[20:21], v[64:65]
	v_and_b32_e32 v57, 0xffff0000, v57
	v_pk_fma_f32 v[52:53], v[4:5], v[72:73], v[52:53]
	s_nop 0
	v_pk_fma_f32 v[52:53], v[24:25], v[56:57], v[52:53]
	s_nop 0
	v_pk_mul_f32 v[72:73], v[52:53], v[50:51]
	v_cvt_pk_bf16_f32 v50, v60, v61
	v_cvt_pk_bf16_f32 v51, v70, v71
	v_cvt_pk_bf16_f32 v52, v74, v75
	v_cvt_pk_bf16_f32 v53, v72, v73
	v_lshl_add_u64 v[60:61], v[148:149], 0, v[158:159]
	global_store_dwordx4 v[60:61], v[50:53], off sc1
	v_pk_mul_f32 v[60:61], v[10:11], v[58:59]
	v_pk_mul_f32 v[70:71], v[18:19], v[68:69]
	s_waitcnt vmcnt(18)
	v_lshlrev_b32_e32 v50, 16, v46
	v_and_b32_e32 v51, 0xffff0000, v46
	v_pk_fma_f32 v[60:61], v[6:7], v[66:67], v[60:61]
	s_waitcnt vmcnt(17)
	v_lshlrev_b32_e32 v52, 16, v42
	v_and_b32_e32 v53, 0xffff0000, v42
	v_pk_fma_f32 v[60:61], v[14:15], v[50:51], v[60:61]
	v_pk_fma_f32 v[70:71], v[2:3], v[76:77], v[70:71]
	v_pk_mul_f32 v[52:53], v[60:61], v[52:53]
	v_lshlrev_b32_e32 v60, 16, v48
	v_and_b32_e32 v61, 0xffff0000, v48
	v_lshlrev_b32_e32 v66, 16, v44
	v_and_b32_e32 v67, 0xffff0000, v44
	v_pk_fma_f32 v[70:71], v[22:23], v[60:61], v[70:71]
	v_lshlrev_b32_e32 v46, 16, v47
	v_pk_mul_f32 v[66:67], v[70:71], v[66:67]
	v_pk_mul_f32 v[70:71], v[12:13], v[54:55]
	v_and_b32_e32 v47, 0xffff0000, v47
	v_pk_fma_f32 v[62:63], v[8:9], v[62:63], v[70:71]
	v_lshlrev_b32_e32 v42, 16, v43
	v_and_b32_e32 v43, 0xffff0000, v43
	v_pk_fma_f32 v[62:63], v[16:17], v[46:47], v[62:63]
	v_lshlrev_b32_e32 v48, 16, v49
	v_pk_mul_f32 v[62:63], v[62:63], v[42:43]
	v_lshlrev_b32_e32 v42, 16, v45
	v_and_b32_e32 v43, 0xffff0000, v45
	v_pk_mul_f32 v[44:45], v[20:21], v[56:57]
	v_and_b32_e32 v49, 0xffff0000, v49
	v_pk_fma_f32 v[44:45], v[4:5], v[64:65], v[44:45]
	s_nop 0
	v_pk_fma_f32 v[44:45], v[24:25], v[48:49], v[44:45]
	s_nop 0
	v_pk_mul_f32 v[64:65], v[44:45], v[42:43]
	v_cvt_pk_bf16_f32 v42, v52, v53
	v_cvt_pk_bf16_f32 v43, v62, v63
	v_cvt_pk_bf16_f32 v44, v66, v67
	v_cvt_pk_bf16_f32 v45, v64, v65
	v_lshl_add_u64 v[52:53], v[148:149], 0, v[156:157]
	global_store_dwordx4 v[52:53], v[42:45], off sc1
	v_pk_mul_f32 v[52:53], v[10:11], v[50:51]
	v_pk_mul_f32 v[62:63], v[18:19], v[60:61]
	s_waitcnt vmcnt(17)
	v_lshlrev_b32_e32 v42, 16, v38
	v_and_b32_e32 v43, 0xffff0000, v38
	v_pk_fma_f32 v[52:53], v[6:7], v[58:59], v[52:53]
	s_waitcnt vmcnt(16)
	v_lshlrev_b32_e32 v44, 16, v34
	v_and_b32_e32 v45, 0xffff0000, v34
	v_pk_fma_f32 v[52:53], v[14:15], v[42:43], v[52:53]
	v_pk_fma_f32 v[62:63], v[2:3], v[68:69], v[62:63]
	v_pk_mul_f32 v[44:45], v[52:53], v[44:45]
	v_lshlrev_b32_e32 v52, 16, v40
	v_and_b32_e32 v53, 0xffff0000, v40
	v_lshlrev_b32_e32 v58, 16, v36
	v_and_b32_e32 v59, 0xffff0000, v36
	v_pk_fma_f32 v[62:63], v[22:23], v[52:53], v[62:63]
	v_lshlrev_b32_e32 v38, 16, v39
	v_pk_mul_f32 v[58:59], v[62:63], v[58:59]
	v_pk_mul_f32 v[62:63], v[12:13], v[46:47]
	v_and_b32_e32 v39, 0xffff0000, v39
	v_pk_fma_f32 v[54:55], v[8:9], v[54:55], v[62:63]
	v_lshlrev_b32_e32 v34, 16, v35
	v_and_b32_e32 v35, 0xffff0000, v35
	v_pk_fma_f32 v[54:55], v[16:17], v[38:39], v[54:55]
	v_lshlrev_b32_e32 v40, 16, v41
	v_pk_mul_f32 v[54:55], v[54:55], v[34:35]
	v_lshlrev_b32_e32 v34, 16, v37
	v_and_b32_e32 v35, 0xffff0000, v37
	v_pk_mul_f32 v[36:37], v[20:21], v[48:49]
	v_and_b32_e32 v41, 0xffff0000, v41
	v_pk_fma_f32 v[36:37], v[4:5], v[56:57], v[36:37]
	v_pk_mul_f32 v[42:43], v[10:11], v[42:43]
	v_pk_fma_f32 v[36:37], v[24:25], v[40:41], v[36:37]
	v_pk_mul_f32 v[38:39], v[12:13], v[38:39]
	v_pk_mul_f32 v[56:57], v[36:37], v[34:35]
	v_cvt_pk_bf16_f32 v34, v44, v45
	v_cvt_pk_bf16_f32 v35, v54, v55
	v_cvt_pk_bf16_f32 v36, v58, v59
	v_cvt_pk_bf16_f32 v37, v56, v57
	v_lshl_add_u64 v[44:45], v[148:149], 0, v[154:155]
	global_store_dwordx4 v[44:45], v[34:37], off sc1
	v_pk_fma_f32 v[42:43], v[6:7], v[50:51], v[42:43]
	v_pk_fma_f32 v[38:39], v[8:9], v[46:47], v[38:39]
	s_waitcnt vmcnt(16)
	v_lshlrev_b32_e32 v34, 16, v30
	v_and_b32_e32 v35, 0xffff0000, v30
	v_lshlrev_b32_e32 v30, 16, v31
	v_and_b32_e32 v31, 0xffff0000, v31
	s_waitcnt vmcnt(15)
	v_lshlrev_b32_e32 v36, 16, v26
	v_and_b32_e32 v37, 0xffff0000, v26
	v_pk_fma_f32 v[34:35], v[14:15], v[34:35], v[42:43]
	v_lshlrev_b32_e32 v26, 16, v27
	v_and_b32_e32 v27, 0xffff0000, v27
	v_pk_fma_f32 v[30:31], v[16:17], v[30:31], v[38:39]
	v_pk_mul_f32 v[34:35], v[34:35], v[36:37]
	v_lshlrev_b32_e32 v36, 16, v32
	v_and_b32_e32 v37, 0xffff0000, v32
	v_pk_mul_f32 v[44:45], v[18:19], v[52:53]
	v_pk_mul_f32 v[30:31], v[30:31], v[26:27]
	v_lshlrev_b32_e32 v26, 16, v33
	v_and_b32_e32 v27, 0xffff0000, v33
	v_pk_mul_f32 v[32:33], v[20:21], v[40:41]
	v_pk_fma_f32 v[44:45], v[2:3], v[60:61], v[44:45]
	v_pk_fma_f32 v[32:33], v[4:5], v[48:49], v[32:33]
	v_lshlrev_b32_e32 v42, 16, v28
	v_and_b32_e32 v43, 0xffff0000, v28
	v_pk_fma_f32 v[36:37], v[22:23], v[36:37], v[44:45]
	v_lshlrev_b32_e32 v28, 16, v29
	v_and_b32_e32 v29, 0xffff0000, v29
	v_pk_fma_f32 v[26:27], v[24:25], v[26:27], v[32:33]
	v_pk_mul_f32 v[36:37], v[36:37], v[42:43]
	v_pk_mul_f32 v[32:33], v[26:27], v[28:29]
	v_cvt_pk_bf16_f32 v26, v34, v35
	v_cvt_pk_bf16_f32 v27, v30, v31
	v_cvt_pk_bf16_f32 v28, v36, v37
	v_cvt_pk_bf16_f32 v29, v32, v33
	v_lshl_add_u64 v[30:31], v[148:149], 0, v[152:153]
	global_store_dwordx4 v[30:31], v[26:29], off sc1
	s_andn2_b64 exec, exec, s[38:39]
	s_cbranch_execz .LBB0_257

; __device__ __forceinline__ void unpack8(const u32x4 w, f32x4& v0, f32x4& v1) { v0 = (f32x4){bf_lo(w.x), bf_hi(w.x), bf_lo(w.y), bf_hi(w.y)}; v1 = (f32x4){bf_lo(w.z), bf_hi(w.z), bf_lo(w.w), bf_hi(w.w)}; }
; __device__ __forceinline__ void conv_items(bf16u* BGb, const bf16u* CGb, const float* cw, int vcup, int G) {
;     ...
;     for (int item = vcup * 4 + qd; item < NTOK / 16; item += G * 4) {
;         const int r0 = item * 16;
;         f32x4 p2a = (f32x4){0.f, 0.f, 0.f, 0.f}, p2b = p2a, p1a = p2a, p1b = p2a;
;         if ((r0 & (SEQL - 1)) != 0) {
;             unpack8(*(const v4u*)(CGb + (size_t)(r0 - 2) * DMOD + c0), p2a, p2b);
;             unpack8(*(const v4u*)(CGb + (size_t)(r0 - 1) * DMOD + c0), p1a, p1b);
;         }
;         v4u pv[16], bv[16];
; #pragma unroll
;         for (int i = 0; i < 16; ++i) { const size_t off = (size_t)(r0 + i) * DMOD + c0; pv[i] = *(const v4u*)(CGb + off); bv[i] = *(const v4u*)(BGb + off); }
.LBB0_347:
	s_or_b64 exec, exec, s[18:19]
	v_add_u32_e32 v26, -15, v150
	v_ashrrev_i32_e32 v27, 31, v26
	v_lshlrev_b64 v[198:199], 11, v[26:27]
	v_or_b32_e32 v26, v198, v0
	v_mov_b32_e32 v27, v199
	v_lshl_add_u64 v[28:29], s[30:31], 0, v[26:27]
	v_lshl_add_u64 v[26:27], s[28:29], 0, v[26:27]
	global_load_dwordx4 v[202:205], v[28:29], off
	global_load_dwordx4 v[206:209], v[26:27], off
	v_add_u32_e32 v26, -14, v150
	v_ashrrev_i32_e32 v27, 31, v26
	v_lshlrev_b64 v[190:191], 11, v[26:27]
	v_or_b32_e32 v26, v190, v0
	v_mov_b32_e32 v27, v191
	v_lshl_add_u64 v[28:29], s[30:31], 0, v[26:27]
	v_lshl_add_u64 v[26:27], s[28:29], 0, v[26:27]
	global_load_dwordx4 v[142:145], v[28:29], off
	global_load_dwordx4 v[138:141], v[26:27], off
	v_add_u32_e32 v26, -13, v150
	v_ashrrev_i32_e32 v27, 31, v26
	v_lshlrev_b64 v[180:181], 11, v[26:27]
	v_or_b32_e32 v26, v180, v0
	v_mov_b32_e32 v27, v181
	v_lshl_add_u64 v[28:29], s[30:31], 0, v[26:27]
	v_lshl_add_u64 v[26:27], s[28:29], 0, v[26:27]
	global_load_dwordx4 v[134:137], v[28:29], off
	global_load_dwordx4 v[130:133], v[26:27], off
	v_add_u32_e32 v26, -12, v150
	v_ashrrev_i32_e32 v27, 31, v26
	v_lshlrev_b64 v[176:177], 11, v[26:27]
	v_or_b32_e32 v26, v176, v0
	v_mov_b32_e32 v27, v177
	v_lshl_add_u64 v[28:29], s[30:31], 0, v[26:27]
	v_lshl_add_u64 v[26:27], s[28:29], 0, v[26:27]
	global_load_dwordx4 v[126:129], v[28:29], off
	global_load_dwordx4 v[122:125], v[26:27], off
	v_add_u32_e32 v26, -11, v150
	v_ashrrev_i32_e32 v27, 31, v26
	v_lshlrev_b64 v[174:175], 11, v[26:27]
	v_or_b32_e32 v26, v174, v0
	v_mov_b32_e32 v27, v175
	v_lshl_add_u64 v[28:29], s[30:31], 0, v[26:27]
	v_lshl_add_u64 v[26:27], s[28:29], 0, v[26:27]
	global_load_dwordx4 v[118:121], v[28:29], off
	global_load_dwordx4 v[114:117], v[26:27], off
	v_add_u32_e32 v26, -10, v150
	v_ashrrev_i32_e32 v27, 31, v26
	v_lshlrev_b64 v[172:173], 11, v[26:27]
	v_or_b32_e32 v26, v172, v0
	v_mov_b32_e32 v27, v173
	v_lshl_add_u64 v[28:29], s[30:31], 0, v[26:27]
	v_lshl_add_u64 v[26:27], s[28:29], 0, v[26:27]
	global_load_dwordx4 v[110:113], v[28:29], off
	global_load_dwordx4 v[106:109], v[26:27], off
	v_add_u32_e32 v26, -9, v150
	v_ashrrev_i32_e32 v27, 31, v26
	v_lshlrev_b64 v[170:171], 11, v[26:27]
	v_or_b32_e32 v26, v170, v0
	v_mov_b32_e32 v27, v171
	v_lshl_add_u64 v[28:29], s[30:31], 0, v[26:27]
	v_lshl_add_u64 v[26:27], s[28:29], 0, v[26:27]
	global_load_dwordx4 v[102:105], v[28:29], off
	global_load_dwordx4 v[98:101], v[26:27], off
	v_add_u32_e32 v26, -8, v150
	v_ashrrev_i32_e32 v27, 31, v26
	v_lshlrev_b64 v[168:169], 11, v[26:27]
	v_or_b32_e32 v26, v168, v0
	v_mov_b32_e32 v27, v169
	v_lshl_add_u64 v[28:29], s[30:31], 0, v[26:27]
	v_lshl_add_u64 v[26:27], s[28:29], 0, v[26:27]
	global_load_dwordx4 v[94:97], v[28:29], off
	global_load_dwordx4 v[90:93], v[26:27], off
	v_add_u32_e32 v26, -7, v150
	v_ashrrev_i32_e32 v27, 31, v26
	v_lshlrev_b64 v[166:167], 11, v[26:27]
	v_or_b32_e32 v26, v166, v0
	v_mov_b32_e32 v27, v167
	v_lshl_add_u64 v[28:29], s[30:31], 0, v[26:27]
	v_lshl_add_u64 v[26:27], s[28:29], 0, v[26:27]
	global_load_dwordx4 v[86:89], v[28:29], off
	global_load_dwordx4 v[82:85], v[26:27], off
	v_add_u32_e32 v26, -6, v150
	v_ashrrev_i32_e32 v27, 31, v26
	v_lshlrev_b64 v[164:165], 11, v[26:27]
	v_or_b32_e32 v26, v164, v0
	v_mov_b32_e32 v27, v165
	v_lshl_add_u64 v[28:29], s[30:31], 0, v[26:27]
	v_lshl_add_u64 v[26:27], s[28:29], 0, v[26:27]
	global_load_dwordx4 v[78:81], v[28:29], off
	global_load_dwordx4 v[74:77], v[26:27], off
	v_add_u32_e32 v26, -5, v150
	v_ashrrev_i32_e32 v27, 31, v26
	v_lshlrev_b64 v[162:163], 11, v[26:27]
	v_or_b32_e32 v26, v162, v0
	v_mov_b32_e32 v27, v163
	v_lshl_add_u64 v[28:29], s[30:31], 0, v[26:27]
	v_lshl_add_u64 v[26:27], s[28:29], 0, v[26:27]
	global_load_dwordx4 v[70:73], v[28:29], off
	global_load_dwordx4 v[66:69], v[26:27], off
	v_add_u32_e32 v26, -4, v150
	v_ashrrev_i32_e32 v27, 31, v26
	v_lshlrev_b64 v[160:161], 11, v[26:27]
	v_or_b32_e32 v26, v160, v0
	v_mov_b32_e32 v27, v161
	v_lshl_add_u64 v[28:29], s[30:31], 0, v[26:27]
	v_lshl_add_u64 v[26:27], s[28:29], 0, v[26:27]
	global_load_dwordx4 v[62:65], v[28:29], off
	global_load_dwordx4 v[58:61], v[26:27], off
	v_add_u32_e32 v26, -3, v150
	v_ashrrev_i32_e32 v27, 31, v26
	v_lshlrev_b64 v[158:159], 11, v[26:27]
	v_or_b32_e32 v26, v158, v0
	v_mov_b32_e32 v27, v159
	v_lshl_add_u64 v[28:29], s[30:31], 0, v[26:27]
	v_lshl_add_u64 v[26:27], s[28:29], 0, v[26:27]
	s_waitcnt vmcnt(27)
	v_pk_mul_f32 v[214:215], v[10:11], v[186:187]
	global_load_dwordx4 v[54:57], v[28:29], off
	global_load_dwordx4 v[50:53], v[26:27], off
	v_add_u32_e32 v26, -2, v150
	s_waitcnt vmcnt(25)
	v_lshlrev_b32_e32 v210, 16, v202
	v_and_b32_e32 v211, 0xffff0000, v202
	v_pk_fma_f32 v[196:197], v[6:7], v[196:197], v[214:215]
	v_ashrrev_i32_e32 v27, 31, v26
	s_waitcnt vmcnt(24)
; __device__ __forceinline__ u32x4 pack8(const f32x4 v0, const f32x4 v1) { u32x4 w; w.x = cvt_pk_bf16(v0[0], v0[1]); w.y = cvt_pk_bf16(v0[2], v0[3]); w.z = cvt_pk_bf16(v1[0], v1[1]); w.w = cvt_pk_bf16(v1[2], v1[3]); return w; }
; __device__ __forceinline__ void unpack8(const u32x4 w, f32x4& v0, f32x4& v1) { v0 = (f32x4){bf_lo(w.x), bf_hi(w.x), bf_lo(w.y), bf_hi(w.y)}; v1 = (f32x4){bf_lo(w.z), bf_hi(w.z), bf_lo(w.w), bf_hi(w.w)}; }
; __device__ __forceinline__ void conv_items(bf16u* BGb, const bf16u* CGb, const float* cw, int vcup, int G) {
;     ...
;         for (int i = 0; i < 16; ++i) { const size_t off = (size_t)(r0 + i) * DMOD + c0; pv[i] = *(const v4u*)(CGb + off); bv[i] = *(const v4u*)(BGb + off); }
; #pragma unroll
;         for (int i = 0; i < 16; ++i) {
;             const size_t off = (size_t)(r0 + i) * DMOD + c0;
;             f32x4 p0a, p0b, ba, bb;
;             unpack8(pv[i], p0a, p0b); unpack8(bv[i], ba, bb);
;             f32x4 ya, yb;
; #pragma unroll
;             for (int e = 0; e < 4; ++e) { ya[e] = ba[e] * (w0[e] * p2a[e] + w1[e] * p1a[e] + w2[e] * p0a[e]); yb[e] = bb[e] * (w0[4 + e] * p2b[e] + w1[4 + e] * p1b[e] + w2[4 + e] * p0b[e]); }
;             *(v4u*)(BGb + off) = pack8(ya, yb);
;             p2a = p1a; p2b = p1b; p1a = p0a; p1b = p0b;
;         }
	v_lshlrev_b32_e32 v212, 16, v206
	v_and_b32_e32 v213, 0xffff0000, v206
	v_pk_fma_f32 v[196:197], v[14:15], v[210:211], v[196:197]
	v_pk_mul_f32 v[216:217], v[18:19], v[184:185]
	v_lshlrev_b64 v[156:157], 11, v[26:27]
	v_pk_mul_f32 v[196:197], v[196:197], v[212:213]
	v_lshlrev_b32_e32 v212, 16, v204
	v_and_b32_e32 v213, 0xffff0000, v204
	v_pk_fma_f32 v[194:195], v[2:3], v[194:195], v[216:217]
	v_or_b32_e32 v26, v156, v0
	v_mov_b32_e32 v27, v157
	v_lshlrev_b32_e32 v214, 16, v208
	v_and_b32_e32 v215, 0xffff0000, v208
	v_pk_fma_f32 v[194:195], v[22:23], v[212:213], v[194:195]
	v_lshl_add_u64 v[28:29], s[30:31], 0, v[26:27]
	v_lshl_add_u64 v[26:27], s[28:29], 0, v[26:27]
	v_pk_mul_f32 v[194:195], v[194:195], v[214:215]
	v_pk_mul_f32 v[214:215], v[12:13], v[182:183]
	global_load_dwordx4 v[46:49], v[28:29], off
	global_load_dwordx4 v[42:45], v[26:27], off
	v_add_u32_e32 v26, -1, v150
	v_lshlrev_b32_e32 v202, 16, v203
	v_and_b32_e32 v203, 0xffff0000, v203
	v_pk_fma_f32 v[192:193], v[8:9], v[192:193], v[214:215]
	v_ashrrev_i32_e32 v27, 31, v26
	v_lshlrev_b32_e32 v206, 16, v207
	v_and_b32_e32 v207, 0xffff0000, v207
	v_pk_fma_f32 v[192:193], v[16:17], v[202:203], v[192:193]
	v_lshlrev_b64 v[154:155], 11, v[26:27]
	v_pk_mul_f32 v[206:207], v[192:193], v[206:207]
	v_lshlrev_b32_e32 v192, 16, v209
	v_and_b32_e32 v193, 0xffff0000, v209
	v_pk_mul_f32 v[208:209], v[20:21], v[178:179]
	v_or_b32_e32 v26, v154, v0
	v_mov_b32_e32 v27, v155
	v_ashrrev_i32_e32 v151, 31, v150
	v_lshlrev_b32_e32 v204, 16, v205
	v_and_b32_e32 v205, 0xffff0000, v205
	v_pk_fma_f32 v[188:189], v[4:5], v[188:189], v[208:209]
	v_lshl_add_u64 v[28:29], s[30:31], 0, v[26:27]
	v_lshl_add_u64 v[26:27], s[28:29], 0, v[26:27]
	v_lshlrev_b64 v[152:153], 11, v[150:151]
	v_pk_fma_f32 v[188:189], v[24:25], v[204:205], v[188:189]
	global_load_dwordx4 v[38:41], v[28:29], off
	global_load_dwordx4 v[34:37], v[26:27], off
	v_or_b32_e32 v26, v152, v0
	v_mov_b32_e32 v27, v153
	v_pk_mul_f32 v[188:189], v[188:189], v[192:193]
	v_lshl_add_u64 v[28:29], s[30:31], 0, v[26:27]
	v_lshl_add_u64 v[26:27], s[28:29], 0, v[26:27]
	v_cvt_pk_bf16_f32 v192, v196, v197
	v_cvt_pk_bf16_f32 v193, v206, v207
	v_cvt_pk_bf16_f32 v194, v194, v195
	v_cvt_pk_bf16_f32 v195, v188, v189
	v_lshl_add_u64 v[188:189], v[148:149], 0, v[198:199]
	global_load_dwordx4 v[30:33], v[28:29], off
	s_nop 0
	global_load_dwordx4 v[26:29], v[26:27], off
	v_pk_mul_f32 v[196:197], v[18:19], v[212:213]
	global_store_dwordx4 v[188:189], v[192:195], off sc1
	s_waitcnt vmcnt(30)
	v_lshlrev_b32_e32 v188, 16, v142
	v_and_b32_e32 v189, 0xffff0000, v142
	v_pk_mul_f32 v[194:195], v[10:11], v[210:211]
	s_waitcnt vmcnt(29)
	v_lshlrev_b32_e32 v192, 16, v138
	v_pk_fma_f32 v[186:187], v[6:7], v[186:187], v[194:195]
	v_and_b32_e32 v193, 0xffff0000, v138
	v_pk_fma_f32 v[186:187], v[14:15], v[188:189], v[186:187]
	v_pk_fma_f32 v[184:185], v[2:3], v[184:185], v[196:197]
	v_pk_mul_f32 v[186:187], v[186:187], v[192:193]
	v_lshlrev_b32_e32 v192, 16, v144
	v_and_b32_e32 v193, 0xffff0000, v144
	v_lshlrev_b32_e32 v194, 16, v140
	v_and_b32_e32 v195, 0xffff0000, v140
	v_pk_fma_f32 v[184:185], v[22:23], v[192:193], v[184:185]
	v_lshlrev_b32_e32 v142, 16, v143
	v_pk_mul_f32 v[184:185], v[184:185], v[194:195]
	v_pk_mul_f32 v[194:195], v[12:13], v[202:203]
	v_and_b32_e32 v143, 0xffff0000, v143
	v_pk_fma_f32 v[182:183], v[8:9], v[182:183], v[194:195]
	v_lshlrev_b32_e32 v138, 16, v139
	v_and_b32_e32 v139, 0xffff0000, v139
	v_pk_fma_f32 v[182:183], v[16:17], v[142:143], v[182:183]
	v_lshlrev_b32_e32 v144, 16, v145
	v_pk_mul_f32 v[182:183], v[182:183], v[138:139]
	v_lshlrev_b32_e32 v138, 16, v141
	v_and_b32_e32 v139, 0xffff0000, v141
	v_pk_mul_f32 v[140:141], v[20:21], v[204:205]
	v_and_b32_e32 v145, 0xffff0000, v145
	v_pk_fma_f32 v[140:141], v[4:5], v[178:179], v[140:141]
	v_add_u32_e32 v200, s89, v200
	v_pk_fma_f32 v[140:141], v[24:25], v[144:145], v[140:141]
	v_cmp_lt_i32_e32 vcc, s10, v200
	v_pk_mul_f32 v[178:179], v[140:141], v[138:139]
	v_cvt_pk_bf16_f32 v138, v186, v187
	v_cvt_pk_bf16_f32 v139, v182, v183
	v_cvt_pk_bf16_f32 v140, v184, v185
	v_cvt_pk_bf16_f32 v141, v178, v179
	v_lshl_add_u64 v[178:179], v[148:149], 0, v[190:191]
	global_store_dwordx4 v[178:179], v[138:141], off sc1
	v_pk_mul_f32 v[178:179], v[10:11], v[188:189]
	v_pk_mul_f32 v[184:185], v[18:19], v[192:193]
	s_waitcnt vmcnt(29)
	v_lshlrev_b32_e32 v138, 16, v134
	v_and_b32_e32 v139, 0xffff0000, v134
	v_pk_fma_f32 v[178:179], v[6:7], v[210:211], v[178:179]
	s_waitcnt vmcnt(28)
	v_lshlrev_b32_e32 v140, 16, v130
	v_and_b32_e32 v141, 0xffff0000, v130
	v_pk_fma_f32 v[178:179], v[14:15], v[138:139], v[178:179]
	v_pk_fma_f32 v[184:185], v[2:3], v[212:213], v[184:185]
	v_pk_mul_f32 v[140:141], v[178:179], v[140:141]
	v_lshlrev_b32_e32 v178, 16, v136
	v_and_b32_e32 v179, 0xffff0000, v136
	v_lshlrev_b32_e32 v182, 16, v132
	v_and_b32_e32 v183, 0xffff0000, v132
	v_pk_fma_f32 v[184:185], v[22:23], v[178:179], v[184:185]
	v_lshlrev_b32_e32 v134, 16, v135
	v_pk_mul_f32 v[182:183], v[184:185], v[182:183]
	v_pk_mul_f32 v[184:185], v[12:13], v[142:143]
	v_and_b32_e32 v135, 0xffff0000, v135
	v_pk_fma_f32 v[184:185], v[8:9], v[202:203], v[184:185]
	v_lshlrev_b32_e32 v130, 16, v131
	v_and_b32_e32 v131, 0xffff0000, v131
	v_pk_fma_f32 v[184:185], v[16:17], v[134:135], v[184:185]
	v_lshlrev_b32_e32 v136, 16, v137
	v_pk_mul_f32 v[184:185], v[184:185], v[130:131]
	v_lshlrev_b32_e32 v130, 16, v133
	v_and_b32_e32 v131, 0xffff0000, v133
	v_pk_mul_f32 v[132:133], v[20:21], v[144:145]
	v_and_b32_e32 v137, 0xffff0000, v137
	v_pk_fma_f32 v[132:133], v[4:5], v[204:205], v[132:133]
	s_or_b64 s[16:17], vcc, s[16:17]
	v_pk_fma_f32 v[132:133], v[24:25], v[136:137], v[132:133]
	v_add_u32_e32 v150, s44, v150
	v_pk_mul_f32 v[186:187], v[132:133], v[130:131]
	v_cvt_pk_bf16_f32 v130, v140, v141
	v_cvt_pk_bf16_f32 v131, v184, v185
	v_cvt_pk_bf16_f32 v132, v182, v183
	v_cvt_pk_bf16_f32 v133, v186, v187
	v_lshl_add_u64 v[140:141], v[148:149], 0, v[180:181]
	global_store_dwordx4 v[140:141], v[130:133], off sc1
	v_pk_mul_f32 v[140:141], v[10:11], v[138:139]
	v_pk_mul_f32 v[182:183], v[18:19], v[178:179]
	s_waitcnt vmcnt(28)
; __device__ __forceinline__ u32x4 pack8(const f32x4 v0, const f32x4 v1) { u32x4 w; w.x = cvt_pk_bf16(v0[0], v0[1]); w.y = cvt_pk_bf16(v0[2], v0[3]); w.z = cvt_pk_bf16(v1[0], v1[1]); w.w = cvt_pk_bf16(v1[2], v1[3]); return w; }
; __device__ __forceinline__ void unpack8(const u32x4 w, f32x4& v0, f32x4& v1) { v0 = (f32x4){bf_lo(w.x), bf_hi(w.x), bf_lo(w.y), bf_hi(w.y)}; v1 = (f32x4){bf_lo(w.z), bf_hi(w.z), bf_lo(w.w), bf_hi(w.w)}; }
; __device__ __forceinline__ void conv_items(bf16u* BGb, const bf16u* CGb, const float* cw, int vcup, int G) {
;     ...
;         for (int i = 0; i < 16; ++i) {
;             const size_t off = (size_t)(r0 + i) * DMOD + c0;
;             f32x4 p0a, p0b, ba, bb;
;             unpack8(pv[i], p0a, p0b); unpack8(bv[i], ba, bb);
;             f32x4 ya, yb;
; #pragma unroll
;             for (int e = 0; e < 4; ++e) { ya[e] = ba[e] * (w0[e] * p2a[e] + w1[e] * p1a[e] + w2[e] * p0a[e]); yb[e] = bb[e] * (w0[4 + e] * p2b[e] + w1[4 + e] * p1b[e] + w2[4 + e] * p0b[e]); }
;             *(v4u*)(BGb + off) = pack8(ya, yb);
;             p2a = p1a; p2b = p1b; p1a = p0a; p1b = p0b;
;         }
	v_lshlrev_b32_e32 v130, 16, v126
	v_and_b32_e32 v131, 0xffff0000, v126
	v_pk_fma_f32 v[140:141], v[6:7], v[188:189], v[140:141]
	s_waitcnt vmcnt(27)
	v_lshlrev_b32_e32 v132, 16, v122
	v_and_b32_e32 v133, 0xffff0000, v122
	v_pk_fma_f32 v[140:141], v[14:15], v[130:131], v[140:141]
	v_pk_fma_f32 v[182:183], v[2:3], v[192:193], v[182:183]
	v_pk_mul_f32 v[132:133], v[140:141], v[132:133]
	v_lshlrev_b32_e32 v140, 16, v128
	v_and_b32_e32 v141, 0xffff0000, v128
	v_lshlrev_b32_e32 v180, 16, v124
	v_and_b32_e32 v181, 0xffff0000, v124
	v_pk_fma_f32 v[182:183], v[22:23], v[140:141], v[182:183]
	v_lshlrev_b32_e32 v126, 16, v127
	v_pk_mul_f32 v[180:181], v[182:183], v[180:181]
	v_pk_mul_f32 v[182:183], v[12:13], v[134:135]
	v_and_b32_e32 v127, 0xffff0000, v127
	v_pk_fma_f32 v[142:143], v[8:9], v[142:143], v[182:183]
	v_lshlrev_b32_e32 v122, 16, v123
	v_and_b32_e32 v123, 0xffff0000, v123
	v_pk_fma_f32 v[142:143], v[16:17], v[126:127], v[142:143]
	v_lshlrev_b32_e32 v128, 16, v129
	v_pk_mul_f32 v[142:143], v[142:143], v[122:123]
	v_lshlrev_b32_e32 v122, 16, v125
	v_and_b32_e32 v123, 0xffff0000, v125
	v_pk_mul_f32 v[124:125], v[20:21], v[136:137]
	v_and_b32_e32 v129, 0xffff0000, v129
	v_pk_fma_f32 v[124:125], v[4:5], v[144:145], v[124:125]
	s_nop 0
	v_pk_fma_f32 v[124:125], v[24:25], v[128:129], v[124:125]
	s_nop 0
	v_pk_mul_f32 v[144:145], v[124:125], v[122:123]
	v_cvt_pk_bf16_f32 v122, v132, v133
	v_cvt_pk_bf16_f32 v123, v142, v143
	v_cvt_pk_bf16_f32 v124, v180, v181
	v_cvt_pk_bf16_f32 v125, v144, v145
	v_lshl_add_u64 v[132:133], v[148:149], 0, v[176:177]
	global_store_dwordx4 v[132:133], v[122:125], off sc1
	v_pk_mul_f32 v[132:133], v[10:11], v[130:131]
	v_pk_mul_f32 v[142:143], v[18:19], v[140:141]
	s_waitcnt vmcnt(27)
	v_lshlrev_b32_e32 v122, 16, v118
	v_and_b32_e32 v123, 0xffff0000, v118
	v_pk_fma_f32 v[132:133], v[6:7], v[138:139], v[132:133]
	s_waitcnt vmcnt(26)
	v_lshlrev_b32_e32 v124, 16, v114
	v_and_b32_e32 v125, 0xffff0000, v114
	v_pk_fma_f32 v[132:133], v[14:15], v[122:123], v[132:133]
	v_pk_fma_f32 v[142:143], v[2:3], v[178:179], v[142:143]
	v_pk_mul_f32 v[124:125], v[132:133], v[124:125]
	v_lshlrev_b32_e32 v132, 16, v120
	v_and_b32_e32 v133, 0xffff0000, v120
	v_lshlrev_b32_e32 v138, 16, v116
	v_and_b32_e32 v139, 0xffff0000, v116
	v_pk_fma_f32 v[142:143], v[22:23], v[132:133], v[142:143]
	v_lshlrev_b32_e32 v118, 16, v119
	v_pk_mul_f32 v[138:139], v[142:143], v[138:139]
	v_pk_mul_f32 v[142:143], v[12:13], v[126:127]
	v_and_b32_e32 v119, 0xffff0000, v119
	v_pk_fma_f32 v[134:135], v[8:9], v[134:135], v[142:143]
	v_lshlrev_b32_e32 v114, 16, v115
	v_and_b32_e32 v115, 0xffff0000, v115
	v_pk_fma_f32 v[134:135], v[16:17], v[118:119], v[134:135]
	v_lshlrev_b32_e32 v120, 16, v121
	v_pk_mul_f32 v[134:135], v[134:135], v[114:115]
	v_lshlrev_b32_e32 v114, 16, v117
	v_and_b32_e32 v115, 0xffff0000, v117
	v_pk_mul_f32 v[116:117], v[20:21], v[128:129]
	v_and_b32_e32 v121, 0xffff0000, v121
	v_pk_fma_f32 v[116:117], v[4:5], v[136:137], v[116:117]
	s_nop 0
	v_pk_fma_f32 v[116:117], v[24:25], v[120:121], v[116:117]
	s_nop 0
	v_pk_mul_f32 v[136:137], v[116:117], v[114:115]
	v_cvt_pk_bf16_f32 v114, v124, v125
	v_cvt_pk_bf16_f32 v115, v134, v135
	v_cvt_pk_bf16_f32 v116, v138, v139
	v_cvt_pk_bf16_f32 v117, v136, v137
	v_lshl_add_u64 v[124:125], v[148:149], 0, v[174:175]
	global_store_dwordx4 v[124:125], v[114:117], off sc1
	v_pk_mul_f32 v[124:125], v[10:11], v[122:123]
	v_pk_mul_f32 v[134:135], v[18:19], v[132:133]
	s_waitcnt vmcnt(26)
	v_lshlrev_b32_e32 v114, 16, v110
	v_and_b32_e32 v115, 0xffff0000, v110
	v_pk_fma_f32 v[124:125], v[6:7], v[130:131], v[124:125]
	s_waitcnt vmcnt(25)
	v_lshlrev_b32_e32 v116, 16, v106
	v_and_b32_e32 v117, 0xffff0000, v106
	v_pk_fma_f32 v[124:125], v[14:15], v[114:115], v[124:125]
	v_pk_fma_f32 v[134:135], v[2:3], v[140:141], v[134:135]
	v_pk_mul_f32 v[116:117], v[124:125], v[116:117]
	v_lshlrev_b32_e32 v124, 16, v112
	v_and_b32_e32 v125, 0xffff0000, v112
	v_lshlrev_b32_e32 v130, 16, v108
	v_and_b32_e32 v131, 0xffff0000, v108
	v_pk_fma_f32 v[134:135], v[22:23], v[124:125], v[134:135]
	v_lshlrev_b32_e32 v110, 16, v111
	v_pk_mul_f32 v[130:131], v[134:135], v[130:131]
	v_pk_mul_f32 v[134:135], v[12:13], v[118:119]
	v_and_b32_e32 v111, 0xffff0000, v111
	v_pk_fma_f32 v[126:127], v[8:9], v[126:127], v[134:135]
	v_lshlrev_b32_e32 v106, 16, v107
	v_and_b32_e32 v107, 0xffff0000, v107
	v_pk_fma_f32 v[126:127], v[16:17], v[110:111], v[126:127]
	v_lshlrev_b32_e32 v112, 16, v113
	v_pk_mul_f32 v[126:127], v[126:127], v[106:107]
	v_lshlrev_b32_e32 v106, 16, v109
	v_and_b32_e32 v107, 0xffff0000, v109
	v_pk_mul_f32 v[108:109], v[20:21], v[120:121]
	v_and_b32_e32 v113, 0xffff0000, v113
	v_pk_fma_f32 v[108:109], v[4:5], v[128:129], v[108:109]
	s_nop 0
	v_pk_fma_f32 v[108:109], v[24:25], v[112:113], v[108:109]
	s_nop 0
	v_pk_mul_f32 v[128:129], v[108:109], v[106:107]
	v_cvt_pk_bf16_f32 v106, v116, v117
	v_cvt_pk_bf16_f32 v107, v126, v127
	v_cvt_pk_bf16_f32 v108, v130, v131
	v_cvt_pk_bf16_f32 v109, v128, v129
	v_lshl_add_u64 v[116:117], v[148:149], 0, v[172:173]
	global_store_dwordx4 v[116:117], v[106:109], off sc1
	v_pk_mul_f32 v[116:117], v[10:11], v[114:115]
	v_pk_mul_f32 v[126:127], v[18:19], v[124:125]
	s_waitcnt vmcnt(25)
	v_lshlrev_b32_e32 v106, 16, v102
	v_and_b32_e32 v107, 0xffff0000, v102
	v_pk_fma_f32 v[116:117], v[6:7], v[122:123], v[116:117]
	s_waitcnt vmcnt(24)
; __device__ __forceinline__ u32x4 pack8(const f32x4 v0, const f32x4 v1) { u32x4 w; w.x = cvt_pk_bf16(v0[0], v0[1]); w.y = cvt_pk_bf16(v0[2], v0[3]); w.z = cvt_pk_bf16(v1[0], v1[1]); w.w = cvt_pk_bf16(v1[2], v1[3]); return w; }
; __device__ __forceinline__ void unpack8(const u32x4 w, f32x4& v0, f32x4& v1) { v0 = (f32x4){bf_lo(w.x), bf_hi(w.x), bf_lo(w.y), bf_hi(w.y)}; v1 = (f32x4){bf_lo(w.z), bf_hi(w.z), bf_lo(w.w), bf_hi(w.w)}; }
; __device__ __forceinline__ void conv_items(bf16u* BGb, const bf16u* CGb, const float* cw, int vcup, int G) {
;     ...
;         for (int i = 0; i < 16; ++i) {
;             const size_t off = (size_t)(r0 + i) * DMOD + c0;
;             f32x4 p0a, p0b, ba, bb;
;             unpack8(pv[i], p0a, p0b); unpack8(bv[i], ba, bb);
;             f32x4 ya, yb;
; #pragma unroll
;             for (int e = 0; e < 4; ++e) { ya[e] = ba[e] * (w0[e] * p2a[e] + w1[e] * p1a[e] + w2[e] * p0a[e]); yb[e] = bb[e] * (w0[4 + e] * p2b[e] + w1[4 + e] * p1b[e] + w2[4 + e] * p0b[e]); }
;             *(v4u*)(BGb + off) = pack8(ya, yb);
;             p2a = p1a; p2b = p1b; p1a = p0a; p1b = p0b;
;         }
	v_lshlrev_b32_e32 v108, 16, v98
	v_and_b32_e32 v109, 0xffff0000, v98
	v_pk_fma_f32 v[116:117], v[14:15], v[106:107], v[116:117]
	v_pk_fma_f32 v[126:127], v[2:3], v[132:133], v[126:127]
	v_pk_mul_f32 v[108:109], v[116:117], v[108:109]
	v_lshlrev_b32_e32 v116, 16, v104
	v_and_b32_e32 v117, 0xffff0000, v104
	v_lshlrev_b32_e32 v122, 16, v100
	v_and_b32_e32 v123, 0xffff0000, v100
	v_pk_fma_f32 v[126:127], v[22:23], v[116:117], v[126:127]
	v_lshlrev_b32_e32 v102, 16, v103
	v_pk_mul_f32 v[122:123], v[126:127], v[122:123]
	v_pk_mul_f32 v[126:127], v[12:13], v[110:111]
	v_and_b32_e32 v103, 0xffff0000, v103
	v_pk_fma_f32 v[118:119], v[8:9], v[118:119], v[126:127]
	v_lshlrev_b32_e32 v98, 16, v99
	v_and_b32_e32 v99, 0xffff0000, v99
	v_pk_fma_f32 v[118:119], v[16:17], v[102:103], v[118:119]
	v_lshlrev_b32_e32 v104, 16, v105
	v_pk_mul_f32 v[118:119], v[118:119], v[98:99]
	v_lshlrev_b32_e32 v98, 16, v101
	v_and_b32_e32 v99, 0xffff0000, v101
	v_pk_mul_f32 v[100:101], v[20:21], v[112:113]
	v_and_b32_e32 v105, 0xffff0000, v105
	v_pk_fma_f32 v[100:101], v[4:5], v[120:121], v[100:101]
	s_nop 0
	v_pk_fma_f32 v[100:101], v[24:25], v[104:105], v[100:101]
	s_nop 0
	v_pk_mul_f32 v[120:121], v[100:101], v[98:99]
	v_cvt_pk_bf16_f32 v98, v108, v109
	v_cvt_pk_bf16_f32 v99, v118, v119
	v_cvt_pk_bf16_f32 v100, v122, v123
	v_cvt_pk_bf16_f32 v101, v120, v121
	v_lshl_add_u64 v[108:109], v[148:149], 0, v[170:171]
	global_store_dwordx4 v[108:109], v[98:101], off sc1
	v_pk_mul_f32 v[108:109], v[10:11], v[106:107]
	v_pk_mul_f32 v[118:119], v[18:19], v[116:117]
	s_waitcnt vmcnt(24)
	v_lshlrev_b32_e32 v98, 16, v94
	v_and_b32_e32 v99, 0xffff0000, v94
	v_pk_fma_f32 v[108:109], v[6:7], v[114:115], v[108:109]
	s_waitcnt vmcnt(23)
	v_lshlrev_b32_e32 v100, 16, v90
	v_and_b32_e32 v101, 0xffff0000, v90
	v_pk_fma_f32 v[108:109], v[14:15], v[98:99], v[108:109]
	v_pk_fma_f32 v[118:119], v[2:3], v[124:125], v[118:119]
	v_pk_mul_f32 v[100:101], v[108:109], v[100:101]
	v_lshlrev_b32_e32 v108, 16, v96
	v_and_b32_e32 v109, 0xffff0000, v96
	v_lshlrev_b32_e32 v114, 16, v92
	v_and_b32_e32 v115, 0xffff0000, v92
	v_pk_fma_f32 v[118:119], v[22:23], v[108:109], v[118:119]
	v_lshlrev_b32_e32 v94, 16, v95
	v_pk_mul_f32 v[114:115], v[118:119], v[114:115]
	v_pk_mul_f32 v[118:119], v[12:13], v[102:103]
	v_and_b32_e32 v95, 0xffff0000, v95
	v_pk_fma_f32 v[110:111], v[8:9], v[110:111], v[118:119]
	v_lshlrev_b32_e32 v90, 16, v91
	v_and_b32_e32 v91, 0xffff0000, v91
	v_pk_fma_f32 v[110:111], v[16:17], v[94:95], v[110:111]
	v_lshlrev_b32_e32 v96, 16, v97
	v_pk_mul_f32 v[110:111], v[110:111], v[90:91]
	v_lshlrev_b32_e32 v90, 16, v93
	v_and_b32_e32 v91, 0xffff0000, v93
	v_pk_mul_f32 v[92:93], v[20:21], v[104:105]
	v_and_b32_e32 v97, 0xffff0000, v97
	v_pk_fma_f32 v[92:93], v[4:5], v[112:113], v[92:93]
	s_nop 0
	v_pk_fma_f32 v[92:93], v[24:25], v[96:97], v[92:93]
	s_nop 0
	v_pk_mul_f32 v[112:113], v[92:93], v[90:91]
	v_cvt_pk_bf16_f32 v90, v100, v101
	v_cvt_pk_bf16_f32 v91, v110, v111
	v_cvt_pk_bf16_f32 v92, v114, v115
	v_cvt_pk_bf16_f32 v93, v112, v113
	v_lshl_add_u64 v[100:101], v[148:149], 0, v[168:169]
	global_store_dwordx4 v[100:101], v[90:93], off sc1
	v_pk_mul_f32 v[100:101], v[10:11], v[98:99]
	v_pk_mul_f32 v[110:111], v[18:19], v[108:109]
	s_waitcnt vmcnt(23)
	v_lshlrev_b32_e32 v90, 16, v86
	v_and_b32_e32 v91, 0xffff0000, v86
	v_pk_fma_f32 v[100:101], v[6:7], v[106:107], v[100:101]
	s_waitcnt vmcnt(22)
	v_lshlrev_b32_e32 v92, 16, v82
	v_and_b32_e32 v93, 0xffff0000, v82
	v_pk_fma_f32 v[100:101], v[14:15], v[90:91], v[100:101]
	v_pk_fma_f32 v[110:111], v[2:3], v[116:117], v[110:111]
	v_pk_mul_f32 v[92:93], v[100:101], v[92:93]
	v_lshlrev_b32_e32 v100, 16, v88
	v_and_b32_e32 v101, 0xffff0000, v88
	v_lshlrev_b32_e32 v106, 16, v84
	v_and_b32_e32 v107, 0xffff0000, v84
	v_pk_fma_f32 v[110:111], v[22:23], v[100:101], v[110:111]
	v_lshlrev_b32_e32 v86, 16, v87
	v_pk_mul_f32 v[106:107], v[110:111], v[106:107]
	v_pk_mul_f32 v[110:111], v[12:13], v[94:95]
	v_and_b32_e32 v87, 0xffff0000, v87
	v_pk_fma_f32 v[102:103], v[8:9], v[102:103], v[110:111]
	v_lshlrev_b32_e32 v82, 16, v83
	v_and_b32_e32 v83, 0xffff0000, v83
	v_pk_fma_f32 v[102:103], v[16:17], v[86:87], v[102:103]
	v_lshlrev_b32_e32 v88, 16, v89
	v_pk_mul_f32 v[102:103], v[102:103], v[82:83]
	v_lshlrev_b32_e32 v82, 16, v85
	v_and_b32_e32 v83, 0xffff0000, v85
	v_pk_mul_f32 v[84:85], v[20:21], v[96:97]
	v_and_b32_e32 v89, 0xffff0000, v89
	v_pk_fma_f32 v[84:85], v[4:5], v[104:105], v[84:85]
	s_nop 0
	v_pk_fma_f32 v[84:85], v[24:25], v[88:89], v[84:85]
	s_nop 0
	v_pk_mul_f32 v[104:105], v[84:85], v[82:83]
	v_cvt_pk_bf16_f32 v82, v92, v93
	v_cvt_pk_bf16_f32 v83, v102, v103
	v_cvt_pk_bf16_f32 v84, v106, v107
	v_cvt_pk_bf16_f32 v85, v104, v105
	v_lshl_add_u64 v[92:93], v[148:149], 0, v[166:167]
	global_store_dwordx4 v[92:93], v[82:85], off sc1
	v_pk_mul_f32 v[92:93], v[10:11], v[90:91]
	v_pk_mul_f32 v[102:103], v[18:19], v[100:101]
	s_waitcnt vmcnt(22)
	v_lshlrev_b32_e32 v82, 16, v78
	v_and_b32_e32 v83, 0xffff0000, v78
	v_pk_fma_f32 v[92:93], v[6:7], v[98:99], v[92:93]
	s_waitcnt vmcnt(21)
; __device__ __forceinline__ u32x4 pack8(const f32x4 v0, const f32x4 v1) { u32x4 w; w.x = cvt_pk_bf16(v0[0], v0[1]); w.y = cvt_pk_bf16(v0[2], v0[3]); w.z = cvt_pk_bf16(v1[0], v1[1]); w.w = cvt_pk_bf16(v1[2], v1[3]); return w; }
; __device__ __forceinline__ void unpack8(const u32x4 w, f32x4& v0, f32x4& v1) { v0 = (f32x4){bf_lo(w.x), bf_hi(w.x), bf_lo(w.y), bf_hi(w.y)}; v1 = (f32x4){bf_lo(w.z), bf_hi(w.z), bf_lo(w.w), bf_hi(w.w)}; }
; __device__ __forceinline__ void conv_items(bf16u* BGb, const bf16u* CGb, const float* cw, int vcup, int G) {
;     ...
;         for (int i = 0; i < 16; ++i) {
;             const size_t off = (size_t)(r0 + i) * DMOD + c0;
;             f32x4 p0a, p0b, ba, bb;
;             unpack8(pv[i], p0a, p0b); unpack8(bv[i], ba, bb);
;             f32x4 ya, yb;
; #pragma unroll
;             for (int e = 0; e < 4; ++e) { ya[e] = ba[e] * (w0[e] * p2a[e] + w1[e] * p1a[e] + w2[e] * p0a[e]); yb[e] = bb[e] * (w0[4 + e] * p2b[e] + w1[4 + e] * p1b[e] + w2[4 + e] * p0b[e]); }
;             *(v4u*)(BGb + off) = pack8(ya, yb);
;             p2a = p1a; p2b = p1b; p1a = p0a; p1b = p0b;
;         }
	v_lshlrev_b32_e32 v84, 16, v74
	v_and_b32_e32 v85, 0xffff0000, v74
	v_pk_fma_f32 v[92:93], v[14:15], v[82:83], v[92:93]
	v_pk_fma_f32 v[102:103], v[2:3], v[108:109], v[102:103]
	v_pk_mul_f32 v[84:85], v[92:93], v[84:85]
	v_lshlrev_b32_e32 v92, 16, v80
	v_and_b32_e32 v93, 0xffff0000, v80
	v_lshlrev_b32_e32 v98, 16, v76
	v_and_b32_e32 v99, 0xffff0000, v76
	v_pk_fma_f32 v[102:103], v[22:23], v[92:93], v[102:103]
	v_lshlrev_b32_e32 v78, 16, v79
	v_pk_mul_f32 v[98:99], v[102:103], v[98:99]
	v_pk_mul_f32 v[102:103], v[12:13], v[86:87]
	v_and_b32_e32 v79, 0xffff0000, v79
	v_pk_fma_f32 v[94:95], v[8:9], v[94:95], v[102:103]
	v_lshlrev_b32_e32 v74, 16, v75
	v_and_b32_e32 v75, 0xffff0000, v75
	v_pk_fma_f32 v[94:95], v[16:17], v[78:79], v[94:95]
	v_lshlrev_b32_e32 v80, 16, v81
	v_pk_mul_f32 v[94:95], v[94:95], v[74:75]
	v_lshlrev_b32_e32 v74, 16, v77
	v_and_b32_e32 v75, 0xffff0000, v77
	v_pk_mul_f32 v[76:77], v[20:21], v[88:89]
	v_and_b32_e32 v81, 0xffff0000, v81
	v_pk_fma_f32 v[76:77], v[4:5], v[96:97], v[76:77]
	s_nop 0
	v_pk_fma_f32 v[76:77], v[24:25], v[80:81], v[76:77]
	s_nop 0
	v_pk_mul_f32 v[96:97], v[76:77], v[74:75]
	v_cvt_pk_bf16_f32 v74, v84, v85
	v_cvt_pk_bf16_f32 v75, v94, v95
	v_cvt_pk_bf16_f32 v76, v98, v99
	v_cvt_pk_bf16_f32 v77, v96, v97
	v_lshl_add_u64 v[84:85], v[148:149], 0, v[164:165]
	global_store_dwordx4 v[84:85], v[74:77], off sc1
	v_pk_mul_f32 v[84:85], v[10:11], v[82:83]
	v_pk_mul_f32 v[94:95], v[18:19], v[92:93]
	s_waitcnt vmcnt(21)
	v_lshlrev_b32_e32 v74, 16, v70
	v_and_b32_e32 v75, 0xffff0000, v70
	v_pk_fma_f32 v[84:85], v[6:7], v[90:91], v[84:85]
	s_waitcnt vmcnt(20)
	v_lshlrev_b32_e32 v76, 16, v66
	v_and_b32_e32 v77, 0xffff0000, v66
	v_pk_fma_f32 v[84:85], v[14:15], v[74:75], v[84:85]
	v_pk_fma_f32 v[94:95], v[2:3], v[100:101], v[94:95]
	v_pk_mul_f32 v[76:77], v[84:85], v[76:77]
	v_lshlrev_b32_e32 v84, 16, v72
	v_and_b32_e32 v85, 0xffff0000, v72
	v_lshlrev_b32_e32 v90, 16, v68
	v_and_b32_e32 v91, 0xffff0000, v68
	v_pk_fma_f32 v[94:95], v[22:23], v[84:85], v[94:95]
	v_lshlrev_b32_e32 v70, 16, v71
	v_pk_mul_f32 v[90:91], v[94:95], v[90:91]
	v_pk_mul_f32 v[94:95], v[12:13], v[78:79]
	v_and_b32_e32 v71, 0xffff0000, v71
	v_pk_fma_f32 v[86:87], v[8:9], v[86:87], v[94:95]
	v_lshlrev_b32_e32 v66, 16, v67
	v_and_b32_e32 v67, 0xffff0000, v67
	v_pk_fma_f32 v[86:87], v[16:17], v[70:71], v[86:87]
	v_lshlrev_b32_e32 v72, 16, v73
	v_pk_mul_f32 v[86:87], v[86:87], v[66:67]
	v_lshlrev_b32_e32 v66, 16, v69
	v_and_b32_e32 v67, 0xffff0000, v69
	v_pk_mul_f32 v[68:69], v[20:21], v[80:81]
	v_and_b32_e32 v73, 0xffff0000, v73
	v_pk_fma_f32 v[68:69], v[4:5], v[88:89], v[68:69]
	s_nop 0
	v_pk_fma_f32 v[68:69], v[24:25], v[72:73], v[68:69]
	s_nop 0
	v_pk_mul_f32 v[88:89], v[68:69], v[66:67]
	v_cvt_pk_bf16_f32 v66, v76, v77
	v_cvt_pk_bf16_f32 v67, v86, v87
	v_cvt_pk_bf16_f32 v68, v90, v91
	v_cvt_pk_bf16_f32 v69, v88, v89
	v_lshl_add_u64 v[76:77], v[148:149], 0, v[162:163]
	global_store_dwordx4 v[76:77], v[66:69], off sc1
	v_pk_mul_f32 v[76:77], v[10:11], v[74:75]
	v_pk_mul_f32 v[86:87], v[18:19], v[84:85]
	s_waitcnt vmcnt(20)
	v_lshlrev_b32_e32 v66, 16, v62
	v_and_b32_e32 v67, 0xffff0000, v62
	v_pk_fma_f32 v[76:77], v[6:7], v[82:83], v[76:77]
	s_waitcnt vmcnt(19)
	v_lshlrev_b32_e32 v68, 16, v58
	v_and_b32_e32 v69, 0xffff0000, v58
	v_pk_fma_f32 v[76:77], v[14:15], v[66:67], v[76:77]
	v_pk_fma_f32 v[86:87], v[2:3], v[92:93], v[86:87]
	v_pk_mul_f32 v[68:69], v[76:77], v[68:69]
	v_lshlrev_b32_e32 v76, 16, v64
	v_and_b32_e32 v77, 0xffff0000, v64
	v_lshlrev_b32_e32 v82, 16, v60
	v_and_b32_e32 v83, 0xffff0000, v60
	v_pk_fma_f32 v[86:87], v[22:23], v[76:77], v[86:87]
	v_lshlrev_b32_e32 v62, 16, v63
	v_pk_mul_f32 v[82:83], v[86:87], v[82:83]
	v_pk_mul_f32 v[86:87], v[12:13], v[70:71]
	v_and_b32_e32 v63, 0xffff0000, v63
	v_pk_fma_f32 v[78:79], v[8:9], v[78:79], v[86:87]
	v_lshlrev_b32_e32 v58, 16, v59
	v_and_b32_e32 v59, 0xffff0000, v59
	v_pk_fma_f32 v[78:79], v[16:17], v[62:63], v[78:79]
	v_lshlrev_b32_e32 v64, 16, v65
	v_pk_mul_f32 v[78:79], v[78:79], v[58:59]
	v_lshlrev_b32_e32 v58, 16, v61
	v_and_b32_e32 v59, 0xffff0000, v61
	v_pk_mul_f32 v[60:61], v[20:21], v[72:73]
	v_and_b32_e32 v65, 0xffff0000, v65
	v_pk_fma_f32 v[60:61], v[4:5], v[80:81], v[60:61]
	s_nop 0
	v_pk_fma_f32 v[60:61], v[24:25], v[64:65], v[60:61]
	s_nop 0
	v_pk_mul_f32 v[80:81], v[60:61], v[58:59]
	v_cvt_pk_bf16_f32 v58, v68, v69
	v_cvt_pk_bf16_f32 v59, v78, v79
	v_cvt_pk_bf16_f32 v60, v82, v83
	v_cvt_pk_bf16_f32 v61, v80, v81
	v_lshl_add_u64 v[68:69], v[148:149], 0, v[160:161]
	global_store_dwordx4 v[68:69], v[58:61], off sc1
	v_pk_mul_f32 v[68:69], v[10:11], v[66:67]
	v_pk_mul_f32 v[78:79], v[18:19], v[76:77]
	s_waitcnt vmcnt(19)
	v_lshlrev_b32_e32 v58, 16, v54
	v_and_b32_e32 v59, 0xffff0000, v54
	v_pk_fma_f32 v[68:69], v[6:7], v[74:75], v[68:69]
	s_waitcnt vmcnt(18)
; __device__ __forceinline__ u32x4 pack8(const f32x4 v0, const f32x4 v1) { u32x4 w; w.x = cvt_pk_bf16(v0[0], v0[1]); w.y = cvt_pk_bf16(v0[2], v0[3]); w.z = cvt_pk_bf16(v1[0], v1[1]); w.w = cvt_pk_bf16(v1[2], v1[3]); return w; }
; __device__ __forceinline__ void unpack8(const u32x4 w, f32x4& v0, f32x4& v1) { v0 = (f32x4){bf_lo(w.x), bf_hi(w.x), bf_lo(w.y), bf_hi(w.y)}; v1 = (f32x4){bf_lo(w.z), bf_hi(w.z), bf_lo(w.w), bf_hi(w.w)}; }
; __device__ __forceinline__ void conv_items(bf16u* BGb, const bf16u* CGb, const float* cw, int vcup, int G) {
;     ...
;         for (int i = 0; i < 16; ++i) {
;             const size_t off = (size_t)(r0 + i) * DMOD + c0;
;             f32x4 p0a, p0b, ba, bb;
;             unpack8(pv[i], p0a, p0b); unpack8(bv[i], ba, bb);
;             f32x4 ya, yb;
; #pragma unroll
;             for (int e = 0; e < 4; ++e) { ya[e] = ba[e] * (w0[e] * p2a[e] + w1[e] * p1a[e] + w2[e] * p0a[e]); yb[e] = bb[e] * (w0[4 + e] * p2b[e] + w1[4 + e] * p1b[e] + w2[4 + e] * p0b[e]); }
;             *(v4u*)(BGb + off) = pack8(ya, yb);
;             p2a = p1a; p2b = p1b; p1a = p0a; p1b = p0b;
;         }
	v_lshlrev_b32_e32 v60, 16, v50
	v_and_b32_e32 v61, 0xffff0000, v50
	v_pk_fma_f32 v[68:69], v[14:15], v[58:59], v[68:69]
	v_pk_fma_f32 v[78:79], v[2:3], v[84:85], v[78:79]
	v_pk_mul_f32 v[60:61], v[68:69], v[60:61]
	v_lshlrev_b32_e32 v68, 16, v56
	v_and_b32_e32 v69, 0xffff0000, v56
	v_lshlrev_b32_e32 v74, 16, v52
	v_and_b32_e32 v75, 0xffff0000, v52
	v_pk_fma_f32 v[78:79], v[22:23], v[68:69], v[78:79]
	v_lshlrev_b32_e32 v54, 16, v55
	v_pk_mul_f32 v[74:75], v[78:79], v[74:75]
	v_pk_mul_f32 v[78:79], v[12:13], v[62:63]
	v_and_b32_e32 v55, 0xffff0000, v55
	v_pk_fma_f32 v[70:71], v[8:9], v[70:71], v[78:79]
	v_lshlrev_b32_e32 v50, 16, v51
	v_and_b32_e32 v51, 0xffff0000, v51
	v_pk_fma_f32 v[70:71], v[16:17], v[54:55], v[70:71]
	v_lshlrev_b32_e32 v56, 16, v57
	v_pk_mul_f32 v[70:71], v[70:71], v[50:51]
	v_lshlrev_b32_e32 v50, 16, v53
	v_and_b32_e32 v51, 0xffff0000, v53
	v_pk_mul_f32 v[52:53], v[20:21], v[64:65]
	v_and_b32_e32 v57, 0xffff0000, v57
	v_pk_fma_f32 v[52:53], v[4:5], v[72:73], v[52:53]
	s_nop 0
	v_pk_fma_f32 v[52:53], v[24:25], v[56:57], v[52:53]
	s_nop 0
	v_pk_mul_f32 v[72:73], v[52:53], v[50:51]
	v_cvt_pk_bf16_f32 v50, v60, v61
	v_cvt_pk_bf16_f32 v51, v70, v71
	v_cvt_pk_bf16_f32 v52, v74, v75
	v_cvt_pk_bf16_f32 v53, v72, v73
	v_lshl_add_u64 v[60:61], v[148:149], 0, v[158:159]
	global_store_dwordx4 v[60:61], v[50:53], off sc1
	v_pk_mul_f32 v[60:61], v[10:11], v[58:59]
	v_pk_mul_f32 v[70:71], v[18:19], v[68:69]
	s_waitcnt vmcnt(18)
	v_lshlrev_b32_e32 v50, 16, v46
	v_and_b32_e32 v51, 0xffff0000, v46
	v_pk_fma_f32 v[60:61], v[6:7], v[66:67], v[60:61]
	s_waitcnt vmcnt(17)
	v_lshlrev_b32_e32 v52, 16, v42
	v_and_b32_e32 v53, 0xffff0000, v42
	v_pk_fma_f32 v[60:61], v[14:15], v[50:51], v[60:61]
	v_pk_fma_f32 v[70:71], v[2:3], v[76:77], v[70:71]
	v_pk_mul_f32 v[52:53], v[60:61], v[52:53]
	v_lshlrev_b32_e32 v60, 16, v48
	v_and_b32_e32 v61, 0xffff0000, v48
	v_lshlrev_b32_e32 v66, 16, v44
	v_and_b32_e32 v67, 0xffff0000, v44
	v_pk_fma_f32 v[70:71], v[22:23], v[60:61], v[70:71]
	v_lshlrev_b32_e32 v46, 16, v47
	v_pk_mul_f32 v[66:67], v[70:71], v[66:67]
	v_pk_mul_f32 v[70:71], v[12:13], v[54:55]
	v_and_b32_e32 v47, 0xffff0000, v47
	v_pk_fma_f32 v[62:63], v[8:9], v[62:63], v[70:71]
	v_lshlrev_b32_e32 v42, 16, v43
	v_and_b32_e32 v43, 0xffff0000, v43
	v_pk_fma_f32 v[62:63], v[16:17], v[46:47], v[62:63]
	v_lshlrev_b32_e32 v48, 16, v49
	v_pk_mul_f32 v[62:63], v[62:63], v[42:43]
	v_lshlrev_b32_e32 v42, 16, v45
	v_and_b32_e32 v43, 0xffff0000, v45
	v_pk_mul_f32 v[44:45], v[20:21], v[56:57]
	v_and_b32_e32 v49, 0xffff0000, v49
	v_pk_fma_f32 v[44:45], v[4:5], v[64:65], v[44:45]
	s_nop 0
	v_pk_fma_f32 v[44:45], v[24:25], v[48:49], v[44:45]
	s_nop 0
	v_pk_mul_f32 v[64:65], v[44:45], v[42:43]
	v_cvt_pk_bf16_f32 v42, v52, v53
	v_cvt_pk_bf16_f32 v43, v62, v63
	v_cvt_pk_bf16_f32 v44, v66, v67
	v_cvt_pk_bf16_f32 v45, v64, v65
	v_lshl_add_u64 v[52:53], v[148:149], 0, v[156:157]
	global_store_dwordx4 v[52:53], v[42:45], off sc1
	v_pk_mul_f32 v[52:53], v[10:11], v[50:51]
	v_pk_mul_f32 v[62:63], v[18:19], v[60:61]
	s_waitcnt vmcnt(17)
	v_lshlrev_b32_e32 v42, 16, v38
	v_and_b32_e32 v43, 0xffff0000, v38
	v_pk_fma_f32 v[52:53], v[6:7], v[58:59], v[52:53]
	s_waitcnt vmcnt(16)
	v_lshlrev_b32_e32 v44, 16, v34
	v_and_b32_e32 v45, 0xffff0000, v34
	v_pk_fma_f32 v[52:53], v[14:15], v[42:43], v[52:53]
	v_pk_fma_f32 v[62:63], v[2:3], v[68:69], v[62:63]
	v_pk_mul_f32 v[44:45], v[52:53], v[44:45]
	v_lshlrev_b32_e32 v52, 16, v40
	v_and_b32_e32 v53, 0xffff0000, v40
	v_lshlrev_b32_e32 v58, 16, v36
	v_and_b32_e32 v59, 0xffff0000, v36
	v_pk_fma_f32 v[62:63], v[22:23], v[52:53], v[62:63]
	v_lshlrev_b32_e32 v38, 16, v39
	v_pk_mul_f32 v[58:59], v[62:63], v[58:59]
	v_pk_mul_f32 v[62:63], v[12:13], v[46:47]
	v_and_b32_e32 v39, 0xffff0000, v39
	v_pk_fma_f32 v[54:55], v[8:9], v[54:55], v[62:63]
	v_lshlrev_b32_e32 v34, 16, v35
	v_and_b32_e32 v35, 0xffff0000, v35
	v_pk_fma_f32 v[54:55], v[16:17], v[38:39], v[54:55]
	v_lshlrev_b32_e32 v40, 16, v41
	v_pk_mul_f32 v[54:55], v[54:55], v[34:35]
	v_lshlrev_b32_e32 v34, 16, v37
	v_and_b32_e32 v35, 0xffff0000, v37
	v_pk_mul_f32 v[36:37], v[20:21], v[48:49]
	v_and_b32_e32 v41, 0xffff0000, v41
	v_pk_fma_f32 v[36:37], v[4:5], v[56:57], v[36:37]
	v_pk_mul_f32 v[42:43], v[10:11], v[42:43]
	v_pk_fma_f32 v[36:37], v[24:25], v[40:41], v[36:37]
	v_pk_mul_f32 v[38:39], v[12:13], v[38:39]
	v_pk_mul_f32 v[56:57], v[36:37], v[34:35]
	v_cvt_pk_bf16_f32 v34, v44, v45
	v_cvt_pk_bf16_f32 v35, v54, v55
	v_cvt_pk_bf16_f32 v36, v58, v59
	v_cvt_pk_bf16_f32 v37, v56, v57
	v_lshl_add_u64 v[44:45], v[148:149], 0, v[154:155]
	global_store_dwordx4 v[44:45], v[34:37], off sc1
	v_pk_fma_f32 v[42:43], v[6:7], v[50:51], v[42:43]
	v_pk_fma_f32 v[38:39], v[8:9], v[46:47], v[38:39]
	s_waitcnt vmcnt(16)
	v_lshlrev_b32_e32 v34, 16, v30
	v_and_b32_e32 v35, 0xffff0000, v30
	v_lshlrev_b32_e32 v30, 16, v31
	v_and_b32_e32 v31, 0xffff0000, v31
	s_waitcnt vmcnt(15)
	v_lshlrev_b32_e32 v36, 16, v26
	v_and_b32_e32 v37, 0xffff0000, v26
	v_pk_fma_f32 v[34:35], v[14:15], v[34:35], v[42:43]
	v_lshlrev_b32_e32 v26, 16, v27
	v_and_b32_e32 v27, 0xffff0000, v27
	v_pk_fma_f32 v[30:31], v[16:17], v[30:31], v[38:39]
	v_pk_mul_f32 v[34:35], v[34:35], v[36:37]
	v_lshlrev_b32_e32 v36, 16, v32
	v_and_b32_e32 v37, 0xffff0000, v32
	v_pk_mul_f32 v[44:45], v[18:19], v[52:53]
	v_pk_mul_f32 v[30:31], v[30:31], v[26:27]
	v_lshlrev_b32_e32 v26, 16, v33
	v_and_b32_e32 v27, 0xffff0000, v33
	v_pk_mul_f32 v[32:33], v[20:21], v[40:41]
	v_pk_fma_f32 v[44:45], v[2:3], v[60:61], v[44:45]
	v_pk_fma_f32 v[32:33], v[4:5], v[48:49], v[32:33]
	v_lshlrev_b32_e32 v42, 16, v28
	v_and_b32_e32 v43, 0xffff0000, v28
	v_pk_fma_f32 v[36:37], v[22:23], v[36:37], v[44:45]
	v_lshlrev_b32_e32 v28, 16, v29
	v_and_b32_e32 v29, 0xffff0000, v29
	v_pk_fma_f32 v[26:27], v[24:25], v[26:27], v[32:33]
	v_pk_mul_f32 v[36:37], v[36:37], v[42:43]
	v_pk_mul_f32 v[32:33], v[26:27], v[28:29]
	v_cvt_pk_bf16_f32 v26, v34, v35
	v_cvt_pk_bf16_f32 v27, v30, v31
	v_cvt_pk_bf16_f32 v28, v36, v37
	v_cvt_pk_bf16_f32 v29, v32, v33
	v_lshl_add_u64 v[30:31], v[148:149], 0, v[152:153]
	global_store_dwordx4 v[30:31], v[26:29], off sc1
	s_andn2_b64 exec, exec, s[16:17]
	s_cbranch_execz .LBB0_350

; #define GSYNC() do { for (int r_ = 0; r_ < REP_SYNC; ++r_) xcd_barrier(bar); } while (0)
; __global__ void __launch_bounds__(NWAVES * 64, 2) mk_fwd(Args a) {
;     ...
;             for (int gidx = vcup; gidx < 512; gidx += G) {
;                 const int gi = gidx >> 8, v = gidx & 255, bh = v >> 3, s = v & 7, qb = gi ? 15 - s : s, b = bh >> 3, h = bh & 7;
;     ...
;         GSYNC();
.LBB0_351:
	s_waitcnt vmcnt(0)
	s_barrier
	s_mov_b64 s[2:3], exec
	v_readlane_b32 s12, v253, 36
	v_readlane_b32 s13, v253, 37
	s_and_b64 s[12:13], s[2:3], s[12:13]
	s_mov_b64 exec, s[12:13]
	s_cbranch_execz .LBB0_403
	s_cmp_lg_u32 s98, 0
	s_cbranch_scc0 .Lgb_full_403
	v_readlane_b32 s4, v253, 0
	v_readlane_b32 s1, v253, 1
	v_readlane_b32 s12, v253, 56
	v_readlane_b32 s13, v253, 57
	s_nop 3
	s_lshr_b32 s16, s4, 6
	s_lshl_b32 s16, s16, 4
	s_and_b32 s17, s4, 7
	s_add_i32 s18, s16, s17
	s_sub_i32 s19, s16, s17
	s_add_i32 s19, s19, 15
	s_lshr_b32 s20, s4, 2
	s_lshl_b32 s18, s18, 6
	s_lshl_b32 s19, s19, 6
	s_lshl_b32 s20, s20, 6
	s_add_i32 s18, s18, 0x5f00
	s_add_i32 s19, s19, 0x5f00
	s_add_i32 s20, s20, 0x5f00
	v_mov_b32_e32 v2, s18
	v_mov_b32_e32 v3, s19
	v_mov_b32_e32 v4, s20
	s_and_b32 s16, s1, 7
	s_lshl_b32 s16, s16, 3
	s_bfe_u32 s17, s1, 0x30003
	s_add_i32 s16, s16, s17
	s_lshl_b32 s16, s16, 6
	s_add_i32 s16, s16, 0x5f00
	v_mov_b32_e32 v5, s16
	s_add_i32 s21, s92, 1
	s_mul_i32 s21, s21, 12
	s_mov_b32 s1, 0
	global_atomic_add v2, v234, s[12:13]
	global_atomic_add v3, v234, s[12:13]
	global_atomic_add v4, v234, s[12:13]
.Lflow_spin_403:
	global_load_dword v6, v5, s[12:13] sc1
	s_waitcnt vmcnt(0)
	v_readfirstlane_b32 s4, v6
	s_nop 3
	s_cmp_ge_u32 s4, s21
	s_cbranch_scc1 .Lflow_done_403
	s_sleep 1
	s_add_i32 s1, s1, 1
	s_cmp_lt_u32 s1, 0x40000
	s_cbranch_scc1 .Lflow_spin_403
